# adds nt cache policy to the up-GEMM (r1) and branch-GEMM (obr) streaming output stores on top of the previous version
# speedup vs baseline: 1.0008x; 1.0008x over previous
; #define PG8_STAGE(bufoff, gbase, voff) do { _Pragma("unroll") for (int _i = 0; _i < 2; ++_i) \
;         __builtin_amdgcn_global_load_lds((const unsigned*)((const char*)(gbase) + (size_t)_i * p64##voff + (v##voff##_)), (LAS unsigned*)(lds + (bufoff) + ldsw + _i * 8192), 16, 0, 0); } while (0)
; #define PG8_LDA(dst, b, h) do { _Pragma("unroll") for (int m = 0; m < 4; ++m) _Pragma("unroll") for (int k = 0; k < 2; ++k) dst[m][k] = *(const LAS bf16x8*)(lds + PG8_SA(b, h) + aoff + m * 2048 + k * 1024); } while (0)
; #define PG8_LDB(dst, b, h) do { _Pragma("unroll") for (int n = 0; n < 2; ++n) _Pragma("unroll") for (int k = 0; k < 2; ++k) dst[n][k] = *(const LAS bf16x8*)(lds + PG8_SB(b, h) + boff + n * 2048 + k * 1024); } while (0)
; #define PG8_MMA(ai, bj, At, Bt) do { __builtin_amdgcn_s_setprio(1); _Pragma("unroll") for (int m = 0; m < 4; ++m) _Pragma("unroll") for (int n = 0; n < 2; ++n) _Pragma("unroll") for (int k = 0; k < 2; ++k) \
;         acc[ai][bj][m][n] = __builtin_amdgcn_mfma_f32_16x16x32_bf16(Bt[n][k], At[m][k], acc[ai][bj][m][n], 0, 0, 0); __builtin_amdgcn_s_setprio(0); } while (0)
; #define PG8_WAIT_V(n) asm volatile("s_waitcnt vmcnt(" #n ")" ::: "memory")
; #define PG8_WAIT_L(n) asm volatile("s_waitcnt lgkmcnt(" #n ")" ::: "memory")
; #define PG8_BAR __builtin_amdgcn_s_barrier()
; #define PG8_SCHED __builtin_amdgcn_sched_barrier(0)
; template <class Epi, class Sched>
; DI void gemm_phase(LAS unsigned char* lds, const Gemm g, const Sched& S, const Epi& E, const int tid) {
;     ...
;             PG8_LDB(B0, 0, 0); PG8_SCHED; PG8_LDA(At, 0, 0); PG8_STAGE(PG8_SA(1, 1), a1 + hstepA, offA);
;             PG8_WAIT_L(8); PG8_BAR; PG8_WAIT_L(0); PG8_MMA(0, 0, At, B0); PG8_BAR; PG8_SCHED;
;             PG8_LDB(B1, 0, 1); PG8_STAGE(PG8_SB(0, 0), b2, offB);
;             PG8_BAR; PG8_WAIT_L(0); PG8_MMA(0, 1, At, B1); PG8_BAR;
;             PG8_LDA(At, 0, 1); PG8_STAGE(PG8_SA(0, 0), a2, offA);
;             PG8_BAR; PG8_WAIT_L(0); PG8_MMA(1, 0, At, B0); PG8_BAR; PG8_SCHED;
;             PG8_STAGE(PG8_SB(0, 1), b2 + hstepB, offB);
;             PG8_WAIT_V(6); PG8_BAR; PG8_MMA(1, 1, At, B1); PG8_BAR;
.LBB0_48:
	s_add_u32 s65, s46, 0xfffc0080
	s_addc_u32 s66, s47, -1
	s_add_i32 s70, 0, 0x10000
	v_add_u32_e32 v132, s70, v147
	ds_read_b128 v[150:153], v132
	ds_read_b128 v[154:157], v132 offset:1024
	ds_read_b128 v[158:161], v132 offset:2048
	ds_read_b128 v[162:165], v132 offset:3072
	s_cmp_eq_u32 s64, 12
	s_cselect_b32 s67, s41, s66
	s_cselect_b32 s66, s62, s65
	s_cselect_b32 s69, s5, s49
	s_cselect_b32 s68, s63, s48
	v_lshl_add_u64 v[132:133], s[46:47], 0, v[130:131]
	s_add_i32 m0, s53, 0xc000
	ds_read_b128 v[166:169], v149
	ds_read_b128 v[170:173], v149 offset:1024
	ds_read_b128 v[174:177], v149 offset:2048
	ds_read_b128 v[178:181], v149 offset:3072
	ds_read_b128 v[182:185], v149 offset:4096
	ds_read_b128 v[186:189], v149 offset:5120
	ds_read_b128 v[190:193], v149 offset:6144
	ds_read_b128 v[214:217], v149 offset:7168
	global_load_lds_dwordx4 v[132:133], off
	v_lshl_add_u64 v[132:133], v[132:133], 0, s[10:11]
	s_add_i32 m0, s53, 0xe000
	s_nop 0
	global_load_lds_dwordx4 v[132:133], off
	s_waitcnt lgkmcnt(8)
	s_barrier
	s_waitcnt lgkmcnt(0)
	s_setprio 1
	s_waitcnt lgkmcnt(0)
	v_mfma_f32_16x16x32_bf16 v[126:129], v[150:153], v[166:169], v[126:129]
	v_mfma_f32_16x16x32_bf16 v[122:125], v[158:161], v[166:169], v[122:125]
	v_mfma_f32_16x16x32_bf16 v[110:113], v[150:153], v[174:177], v[110:113]
	v_mfma_f32_16x16x32_bf16 v[106:109], v[158:161], v[174:177], v[106:109]
	v_mfma_f32_16x16x32_bf16 v[94:97], v[150:153], v[182:185], v[94:97]
	v_mfma_f32_16x16x32_bf16 v[90:93], v[158:161], v[182:185], v[90:93]
	v_mfma_f32_16x16x32_bf16 v[78:81], v[150:153], v[190:193], v[78:81]
	v_mfma_f32_16x16x32_bf16 v[74:77], v[158:161], v[190:193], v[74:77]
	v_mfma_f32_16x16x32_bf16 v[126:129], v[154:157], v[170:173], v[126:129]
	v_mfma_f32_16x16x32_bf16 v[122:125], v[162:165], v[170:173], v[122:125]
	v_mfma_f32_16x16x32_bf16 v[110:113], v[154:157], v[178:181], v[110:113]
	v_mfma_f32_16x16x32_bf16 v[106:109], v[162:165], v[178:181], v[106:109]
	v_mfma_f32_16x16x32_bf16 v[94:97], v[154:157], v[186:189], v[94:97]
	v_mfma_f32_16x16x32_bf16 v[90:93], v[162:165], v[186:189], v[90:93]
	v_mfma_f32_16x16x32_bf16 v[78:81], v[154:157], v[214:217], v[78:81]
	v_mfma_f32_16x16x32_bf16 v[74:77], v[162:165], v[214:217], v[74:77]
	s_setprio 0
	s_barrier
	s_add_i32 s65, 0, 0x14000
	v_add_u32_e32 v132, s65, v147
	ds_read_b128 v[218:221], v132
	ds_read_b128 v[222:225], v132 offset:1024
	ds_read_b128 v[226:229], v132 offset:2048
	ds_read_b128 v[244:247], v132 offset:3072
	v_lshl_add_u64 v[132:133], s[68:69], 0, v[0:1]
	s_add_i32 s68, s70, s52
	s_mov_b32 m0, s68
	v_lshl_add_u64 v[198:199], v[132:133], 0, s[10:11]
	global_load_lds_dwordx4 v[132:133], off
	s_add_i32 m0, s68, 0x2000
	s_nop 0
	global_load_lds_dwordx4 v[198:199], off
	s_barrier
	s_waitcnt lgkmcnt(0)
	s_setprio 1
	s_waitcnt lgkmcnt(0)
	v_mfma_f32_16x16x32_bf16 v[118:121], v[218:221], v[166:169], v[118:121]
	v_mfma_f32_16x16x32_bf16 v[114:117], v[226:229], v[166:169], v[114:117]
	v_mfma_f32_16x16x32_bf16 v[102:105], v[218:221], v[174:177], v[102:105]
	v_mfma_f32_16x16x32_bf16 v[98:101], v[226:229], v[174:177], v[98:101]
	v_mfma_f32_16x16x32_bf16 v[86:89], v[218:221], v[182:185], v[86:89]
	v_mfma_f32_16x16x32_bf16 v[82:85], v[226:229], v[182:185], v[82:85]
	v_mfma_f32_16x16x32_bf16 v[70:73], v[218:221], v[190:193], v[70:73]
	v_mfma_f32_16x16x32_bf16 v[66:69], v[226:229], v[190:193], v[66:69]
	v_mfma_f32_16x16x32_bf16 v[118:121], v[222:225], v[170:173], v[118:121]
	v_mfma_f32_16x16x32_bf16 v[114:117], v[244:247], v[170:173], v[114:117]
	v_mfma_f32_16x16x32_bf16 v[102:105], v[222:225], v[178:181], v[102:105]
	v_mfma_f32_16x16x32_bf16 v[98:101], v[244:247], v[178:181], v[98:101]
	v_mfma_f32_16x16x32_bf16 v[86:89], v[222:225], v[186:189], v[86:89]
	v_mfma_f32_16x16x32_bf16 v[82:85], v[244:247], v[186:189], v[82:85]
	v_mfma_f32_16x16x32_bf16 v[70:73], v[222:225], v[214:217], v[70:73]
	v_mfma_f32_16x16x32_bf16 v[66:69], v[244:247], v[214:217], v[66:69]
	s_setprio 0
	s_mov_b32 m0, s53
	v_lshl_add_u64 v[198:199], s[66:67], 0, v[212:213]
	s_barrier
	ds_read_b128 v[166:169], v149 offset:16384
	ds_read_b128 v[170:173], v149 offset:17408
	ds_read_b128 v[174:177], v149 offset:18432
	ds_read_b128 v[178:181], v149 offset:19456
	ds_read_b128 v[182:185], v149 offset:20480
	ds_read_b128 v[186:189], v149 offset:21504
	ds_read_b128 v[190:193], v149 offset:22528
	ds_read_b128 v[214:217], v149 offset:23552
	global_load_lds_dwordx4 v[198:199], off
	v_lshl_add_u64 v[200:201], v[198:199], 0, s[10:11]
	s_mov_b32 m0, s54
	s_nop 0
	global_load_lds_dwordx4 v[200:201], off
	s_barrier
	s_waitcnt lgkmcnt(0)
	s_setprio 1
	s_waitcnt lgkmcnt(0)
	v_mfma_f32_16x16x32_bf16 v[62:65], v[150:153], v[166:169], v[62:65]
	v_mfma_f32_16x16x32_bf16 v[58:61], v[158:161], v[166:169], v[58:61]
	v_mfma_f32_16x16x32_bf16 v[46:49], v[150:153], v[174:177], v[46:49]
	v_mfma_f32_16x16x32_bf16 v[42:45], v[158:161], v[174:177], v[42:45]
	v_mfma_f32_16x16x32_bf16 v[30:33], v[150:153], v[182:185], v[30:33]
	v_mfma_f32_16x16x32_bf16 v[26:29], v[158:161], v[182:185], v[26:29]
	v_mfma_f32_16x16x32_bf16 v[14:17], v[150:153], v[190:193], v[14:17]
	v_mfma_f32_16x16x32_bf16 v[10:13], v[158:161], v[190:193], v[10:13]
	v_mfma_f32_16x16x32_bf16 v[62:65], v[154:157], v[170:173], v[62:65]
	v_mfma_f32_16x16x32_bf16 v[58:61], v[162:165], v[170:173], v[58:61]
	v_mfma_f32_16x16x32_bf16 v[46:49], v[154:157], v[178:181], v[46:49]
	v_mfma_f32_16x16x32_bf16 v[42:45], v[162:165], v[178:181], v[42:45]
	v_mfma_f32_16x16x32_bf16 v[30:33], v[154:157], v[186:189], v[30:33]
	v_mfma_f32_16x16x32_bf16 v[26:29], v[162:165], v[186:189], v[26:29]
	v_mfma_f32_16x16x32_bf16 v[14:17], v[154:157], v[214:217], v[14:17]
	v_mfma_f32_16x16x32_bf16 v[10:13], v[162:165], v[214:217], v[10:13]
	s_setprio 0
	s_barrier
; #define PG8_STAGE(bufoff, gbase, voff) do { _Pragma("unroll") for (int _i = 0; _i < 2; ++_i) \
;         __builtin_amdgcn_global_load_lds((const unsigned*)((const char*)(gbase) + (size_t)_i * p64##voff + (v##voff##_)), (LAS unsigned*)(lds + (bufoff) + ldsw + _i * 8192), 16, 0, 0); } while (0)
; #define PG8_LDA(dst, b, h) do { _Pragma("unroll") for (int m = 0; m < 4; ++m) _Pragma("unroll") for (int k = 0; k < 2; ++k) dst[m][k] = *(const LAS bf16x8*)(lds + PG8_SA(b, h) + aoff + m * 2048 + k * 1024); } while (0)
; #define PG8_LDB(dst, b, h) do { _Pragma("unroll") for (int n = 0; n < 2; ++n) _Pragma("unroll") for (int k = 0; k < 2; ++k) dst[n][k] = *(const LAS bf16x8*)(lds + PG8_SB(b, h) + boff + n * 2048 + k * 1024); } while (0)
; #define PG8_MMA(ai, bj, At, Bt) do { __builtin_amdgcn_s_setprio(1); _Pragma("unroll") for (int m = 0; m < 4; ++m) _Pragma("unroll") for (int n = 0; n < 2; ++n) _Pragma("unroll") for (int k = 0; k < 2; ++k) \
;         acc[ai][bj][m][n] = __builtin_amdgcn_mfma_f32_16x16x32_bf16(Bt[n][k], At[m][k], acc[ai][bj][m][n], 0, 0, 0); __builtin_amdgcn_s_setprio(0); } while (0)
; #define PG8_WAIT_V(n) asm volatile("s_waitcnt vmcnt(" #n ")" ::: "memory")
; #define PG8_WAIT_L(n) asm volatile("s_waitcnt lgkmcnt(" #n ")" ::: "memory")
; #define PG8_BAR __builtin_amdgcn_s_barrier()
; #define PG8_SCHED __builtin_amdgcn_sched_barrier(0)
; template <class Epi, class Sched>
; DI void gemm_phase(LAS unsigned char* lds, const Gemm g, const Sched& S, const Epi& E, const int tid) {
;     ...
;             PG8_STAGE(PG8_SB(0, 1), b2 + hstepB, offB);
;             PG8_WAIT_V(6); PG8_BAR; PG8_MMA(1, 1, At, B1); PG8_BAR;
;             PG8_LDB(B0, 1, 0); PG8_SCHED; PG8_LDA(At, 1, 0); PG8_STAGE(PG8_SA(0, 1), a2 + hstepA, offA);
;             PG8_WAIT_L(8); PG8_BAR; PG8_WAIT_L(0); PG8_MMA(0, 0, At, B0); PG8_BAR; PG8_SCHED;
;             PG8_LDB(B1, 1, 1); PG8_STAGE(PG8_SB(1, 0), b3, offB);
;             PG8_BAR; PG8_WAIT_L(0); PG8_MMA(0, 1, At, B1); PG8_BAR;
;             PG8_LDA(At, 1, 1); PG8_STAGE(PG8_SA(1, 0), a3, offA);
;             PG8_BAR; PG8_WAIT_L(0); PG8_MMA(1, 0, At, B0); PG8_BAR; PG8_SCHED;
	s_add_i32 s65, s65, s52
	v_lshl_add_u64 v[150:151], v[132:133], 0, s[24:25]
	s_mov_b32 m0, s65
	s_nop 0
	global_load_lds_dwordx4 v[150:151], off
	v_lshl_add_u64 v[150:151], v[132:133], 0, s[28:29]
	s_add_i32 m0, s65, 0x2000
	s_nop 0
	global_load_lds_dwordx4 v[150:151], off
	s_waitcnt vmcnt(6)
	s_barrier
	s_setprio 1
	v_mfma_f32_16x16x32_bf16 v[54:57], v[218:221], v[166:169], v[54:57]
	v_mfma_f32_16x16x32_bf16 v[50:53], v[226:229], v[166:169], v[50:53]
	v_mfma_f32_16x16x32_bf16 v[38:41], v[218:221], v[174:177], v[38:41]
	v_mfma_f32_16x16x32_bf16 v[34:37], v[226:229], v[174:177], v[34:37]
	v_mfma_f32_16x16x32_bf16 v[22:25], v[218:221], v[182:185], v[22:25]
	v_mfma_f32_16x16x32_bf16 v[18:21], v[226:229], v[182:185], v[18:21]
	v_mfma_f32_16x16x32_bf16 v[6:9], v[218:221], v[190:193], v[6:9]
	v_mfma_f32_16x16x32_bf16 v[2:5], v[226:229], v[190:193], v[2:5]
	v_mfma_f32_16x16x32_bf16 v[54:57], v[222:225], v[170:173], v[54:57]
	v_mfma_f32_16x16x32_bf16 v[50:53], v[244:247], v[170:173], v[50:53]
	v_mfma_f32_16x16x32_bf16 v[38:41], v[222:225], v[178:181], v[38:41]
	v_mfma_f32_16x16x32_bf16 v[34:37], v[244:247], v[178:181], v[34:37]
	v_mfma_f32_16x16x32_bf16 v[22:25], v[222:225], v[186:189], v[22:25]
	v_mfma_f32_16x16x32_bf16 v[18:21], v[244:247], v[186:189], v[18:21]
	v_mfma_f32_16x16x32_bf16 v[6:9], v[222:225], v[214:217], v[6:9]
	v_mfma_f32_16x16x32_bf16 v[2:5], v[244:247], v[214:217], v[2:5]
	s_setprio 0
	s_add_i32 s65, 0, 0x18000
	v_add_u32_e32 v162, s65, v147
	s_barrier
	ds_read_b128 v[150:153], v162
	ds_read_b128 v[154:157], v162 offset:1024
	ds_read_b128 v[158:161], v162 offset:2048
	ds_read_b128 v[162:165], v162 offset:3072
	s_mov_b32 m0, s55
	v_lshl_add_u64 v[200:201], v[198:199], 0, s[24:25]
	ds_read_b128 v[166:169], v149 offset:32768
	ds_read_b128 v[170:173], v149 offset:33792
	ds_read_b128 v[174:177], v149 offset:34816
	ds_read_b128 v[178:181], v149 offset:35840
	ds_read_b128 v[182:185], v149 offset:36864
	ds_read_b128 v[186:189], v149 offset:37888
	ds_read_b128 v[190:193], v149 offset:38912
	ds_read_b128 v[214:217], v149 offset:39936
	global_load_lds_dwordx4 v[200:201], off
	v_lshl_add_u64 v[200:201], v[198:199], 0, s[28:29]
	s_mov_b32 m0, s56
	s_nop 0
	global_load_lds_dwordx4 v[200:201], off
	s_waitcnt lgkmcnt(8)
	s_barrier
	s_waitcnt lgkmcnt(0)
	s_setprio 1
	s_waitcnt lgkmcnt(0)
	v_mfma_f32_16x16x32_bf16 v[126:129], v[150:153], v[166:169], v[126:129]
	v_mfma_f32_16x16x32_bf16 v[122:125], v[158:161], v[166:169], v[122:125]
	v_mfma_f32_16x16x32_bf16 v[110:113], v[150:153], v[174:177], v[110:113]
	v_mfma_f32_16x16x32_bf16 v[106:109], v[158:161], v[174:177], v[106:109]
	v_mfma_f32_16x16x32_bf16 v[94:97], v[150:153], v[182:185], v[94:97]
	v_mfma_f32_16x16x32_bf16 v[90:93], v[158:161], v[182:185], v[90:93]
	v_mfma_f32_16x16x32_bf16 v[78:81], v[150:153], v[190:193], v[78:81]
	v_mfma_f32_16x16x32_bf16 v[74:77], v[158:161], v[190:193], v[74:77]
	v_mfma_f32_16x16x32_bf16 v[126:129], v[154:157], v[170:173], v[126:129]
	v_mfma_f32_16x16x32_bf16 v[122:125], v[162:165], v[170:173], v[122:125]
	v_mfma_f32_16x16x32_bf16 v[110:113], v[154:157], v[178:181], v[110:113]
	v_mfma_f32_16x16x32_bf16 v[106:109], v[162:165], v[178:181], v[106:109]
	v_mfma_f32_16x16x32_bf16 v[94:97], v[154:157], v[186:189], v[94:97]
	v_mfma_f32_16x16x32_bf16 v[90:93], v[162:165], v[186:189], v[90:93]
	v_mfma_f32_16x16x32_bf16 v[78:81], v[154:157], v[214:217], v[78:81]
	v_mfma_f32_16x16x32_bf16 v[74:77], v[162:165], v[214:217], v[74:77]
	s_setprio 0
	s_barrier
	s_add_i32 s66, 0, 0x1c000
	v_add_u32_e32 v200, s66, v147
	s_add_i32 s65, s65, s52
	ds_read_b128 v[218:221], v200
	ds_read_b128 v[222:225], v200 offset:1024
	ds_read_b128 v[226:229], v200 offset:2048
	ds_read_b128 v[244:247], v200 offset:3072
	v_lshl_add_u64 v[200:201], v[132:133], 0, s[26:27]
	s_mov_b32 m0, s65
	s_nop 0
	global_load_lds_dwordx4 v[200:201], off
	v_lshl_add_u64 v[200:201], v[132:133], 0, s[36:37]
	s_add_i32 m0, s65, 0x2000
	s_nop 0
	global_load_lds_dwordx4 v[200:201], off
	s_barrier
	s_waitcnt lgkmcnt(0)
	s_setprio 1
	s_waitcnt lgkmcnt(0)
	v_mfma_f32_16x16x32_bf16 v[118:121], v[218:221], v[166:169], v[118:121]
	v_mfma_f32_16x16x32_bf16 v[114:117], v[226:229], v[166:169], v[114:117]
	v_mfma_f32_16x16x32_bf16 v[102:105], v[218:221], v[174:177], v[102:105]
	v_mfma_f32_16x16x32_bf16 v[98:101], v[226:229], v[174:177], v[98:101]
	v_mfma_f32_16x16x32_bf16 v[86:89], v[218:221], v[182:185], v[86:89]
	v_mfma_f32_16x16x32_bf16 v[82:85], v[226:229], v[182:185], v[82:85]
	v_mfma_f32_16x16x32_bf16 v[70:73], v[218:221], v[190:193], v[70:73]
	v_mfma_f32_16x16x32_bf16 v[66:69], v[226:229], v[190:193], v[66:69]
	v_mfma_f32_16x16x32_bf16 v[118:121], v[222:225], v[170:173], v[118:121]
	v_mfma_f32_16x16x32_bf16 v[114:117], v[244:247], v[170:173], v[114:117]
	v_mfma_f32_16x16x32_bf16 v[102:105], v[222:225], v[178:181], v[102:105]
	v_mfma_f32_16x16x32_bf16 v[98:101], v[244:247], v[178:181], v[98:101]
	v_mfma_f32_16x16x32_bf16 v[86:89], v[222:225], v[186:189], v[86:89]
	v_mfma_f32_16x16x32_bf16 v[82:85], v[244:247], v[186:189], v[82:85]
	v_mfma_f32_16x16x32_bf16 v[70:73], v[222:225], v[214:217], v[70:73]
	v_mfma_f32_16x16x32_bf16 v[66:69], v[244:247], v[214:217], v[66:69]
	s_setprio 0
	s_mov_b32 m0, s57
	v_lshl_add_u64 v[200:201], v[198:199], 0, s[26:27]
	s_barrier
	ds_read_b128 v[166:169], v149 offset:49152
	ds_read_b128 v[170:173], v149 offset:50176
	ds_read_b128 v[174:177], v149 offset:51200
	ds_read_b128 v[178:181], v149 offset:52224
	ds_read_b128 v[182:185], v149 offset:53248
	ds_read_b128 v[186:189], v149 offset:54272
	ds_read_b128 v[190:193], v149 offset:55296
	ds_read_b128 v[214:217], v149 offset:56320
	global_load_lds_dwordx4 v[200:201], off
	v_lshl_add_u64 v[198:199], v[198:199], 0, s[36:37]
	s_mov_b32 m0, s58
	s_nop 0
	global_load_lds_dwordx4 v[198:199], off
	s_barrier
; DI unsigned pk2(float lo, float hi) { f32x2 v = {lo, hi}; bf2_t b = __builtin_convertvector(v, bf2_t); return __builtin_bit_cast(unsigned, b); }
; #define PG8_STAGE(bufoff, gbase, voff) do { _Pragma("unroll") for (int _i = 0; _i < 2; ++_i) \
;         __builtin_amdgcn_global_load_lds((const unsigned*)((const char*)(gbase) + (size_t)_i * p64##voff + (v##voff##_)), (LAS unsigned*)(lds + (bufoff) + ldsw + _i * 8192), 16, 0, 0); } while (0)
; #define PG8_MMA(ai, bj, At, Bt) do { __builtin_amdgcn_s_setprio(1); _Pragma("unroll") for (int m = 0; m < 4; ++m) _Pragma("unroll") for (int n = 0; n < 2; ++n) _Pragma("unroll") for (int k = 0; k < 2; ++k) \
;         acc[ai][bj][m][n] = __builtin_amdgcn_mfma_f32_16x16x32_bf16(Bt[n][k], At[m][k], acc[ai][bj][m][n], 0, 0, 0); __builtin_amdgcn_s_setprio(0); } while (0)
; #define PG8_WAIT_V(n) asm volatile("s_waitcnt vmcnt(" #n ")" ::: "memory")
; #define PG8_WAIT_L(n) asm volatile("s_waitcnt lgkmcnt(" #n ")" ::: "memory")
; #define PG8_BAR __builtin_amdgcn_s_barrier()
; #define PG8_SCHED __builtin_amdgcn_sched_barrier(0)
;     DI void operator()(const f32x4 (&acc)[2][2][4][2], const Unit& u, int wr, int wc, int fr, int fq) const {
;         const int row0 = u.pm * BM + wr * 64 + fr, col0 = u.pn * BM + wc * 32 + 8 * fq;
; #pragma unroll
;         for (int ai = 0; ai < 2; ++ai)
; #pragma unroll
;             for (int m = 0; m < 4; ++m) { bf16_t* rowp = O + (size_t)(row0 + ai * HALF + m * 16) * ldc + col0;
; #pragma unroll
;                 for (int bj = 0; bj < 2; ++bj) { f32x4 v0 = acc[ai][bj][m][0], v1 = acc[ai][bj][m][1];
;                     if (ACT == 1) {
; #pragma unroll
;                         for (int j = 0; j < 4; ++j) { float a = fmaxf(v0[j], 0.f), b = fmaxf(v1[j], 0.f); v0[j] = a * a; v1[j] = b * b; } }
;                     u32x4 w; w.x = pk2(v0[0], v0[1]); w.y = pk2(v0[2], v0[3]); w.z = pk2(v1[0], v1[1]); w.w = pk2(v1[2], v1[3]);
;                     *(u32x4*)(rowp + bj * HALF) = w; } }
; template <class Epi, class Sched>
; DI void gemm_phase(LAS unsigned char* lds, const Gemm g, const Sched& S, const Epi& E, const int tid) {
;     ...
;             PG8_BAR; PG8_WAIT_L(0); PG8_MMA(1, 0, At, B0); PG8_BAR; PG8_SCHED;
;             PG8_STAGE(PG8_SB(1, 1), b3 + hstepB, offB);
;             PG8_WAIT_V(6); PG8_BAR; PG8_MMA(1, 1, At, B1); PG8_BAR;
	s_waitcnt lgkmcnt(0)
	s_setprio 1
	s_waitcnt lgkmcnt(0)
	v_mfma_f32_16x16x32_bf16 v[62:65], v[150:153], v[166:169], v[62:65]
	v_mfma_f32_16x16x32_bf16 v[58:61], v[158:161], v[166:169], v[58:61]
	v_mfma_f32_16x16x32_bf16 v[46:49], v[150:153], v[174:177], v[46:49]
	v_mfma_f32_16x16x32_bf16 v[42:45], v[158:161], v[174:177], v[42:45]
	v_mfma_f32_16x16x32_bf16 v[30:33], v[150:153], v[182:185], v[30:33]
	v_mfma_f32_16x16x32_bf16 v[26:29], v[158:161], v[182:185], v[26:29]
	v_mfma_f32_16x16x32_bf16 v[14:17], v[150:153], v[190:193], v[14:17]
	v_mfma_f32_16x16x32_bf16 v[10:13], v[158:161], v[190:193], v[10:13]
	v_mfma_f32_16x16x32_bf16 v[62:65], v[154:157], v[170:173], v[62:65]
	v_mfma_f32_16x16x32_bf16 v[58:61], v[162:165], v[170:173], v[58:61]
	v_mfma_f32_16x16x32_bf16 v[46:49], v[154:157], v[178:181], v[46:49]
	v_mfma_f32_16x16x32_bf16 v[42:45], v[162:165], v[178:181], v[42:45]
	v_mfma_f32_16x16x32_bf16 v[30:33], v[154:157], v[186:189], v[30:33]
	v_mfma_f32_16x16x32_bf16 v[26:29], v[162:165], v[186:189], v[26:29]
	v_mfma_f32_16x16x32_bf16 v[14:17], v[154:157], v[214:217], v[14:17]
	v_mfma_f32_16x16x32_bf16 v[10:13], v[162:165], v[214:217], v[10:13]
	s_setprio 0
	s_barrier
	s_add_i32 s65, s66, s52
	v_lshl_add_u64 v[150:151], v[132:133], 0, s[34:35]
	s_mov_b32 m0, s65
	v_lshl_add_u64 v[132:133], v[132:133], 0, s[18:19]
	global_load_lds_dwordx4 v[150:151], off
	s_add_i32 m0, s65, 0x2000
	s_nop 0
	global_load_lds_dwordx4 v[132:133], off
	s_waitcnt vmcnt(6)
	s_barrier
	s_setprio 1
	v_mfma_f32_16x16x32_bf16 v[54:57], v[218:221], v[166:169], v[54:57]
	v_mfma_f32_16x16x32_bf16 v[50:53], v[226:229], v[166:169], v[50:53]
	v_mfma_f32_16x16x32_bf16 v[38:41], v[218:221], v[174:177], v[38:41]
	v_mfma_f32_16x16x32_bf16 v[34:37], v[226:229], v[174:177], v[34:37]
	v_mfma_f32_16x16x32_bf16 v[22:25], v[218:221], v[182:185], v[22:25]
	v_mfma_f32_16x16x32_bf16 v[18:21], v[226:229], v[182:185], v[18:21]
	v_mfma_f32_16x16x32_bf16 v[6:9], v[218:221], v[190:193], v[6:9]
	v_mfma_f32_16x16x32_bf16 v[2:5], v[226:229], v[190:193], v[2:5]
	v_mfma_f32_16x16x32_bf16 v[54:57], v[222:225], v[170:173], v[54:57]
	v_mfma_f32_16x16x32_bf16 v[50:53], v[244:247], v[170:173], v[50:53]
	v_mfma_f32_16x16x32_bf16 v[38:41], v[222:225], v[178:181], v[38:41]
	v_mfma_f32_16x16x32_bf16 v[34:37], v[244:247], v[178:181], v[34:37]
	v_mfma_f32_16x16x32_bf16 v[22:25], v[222:225], v[186:189], v[22:25]
	v_mfma_f32_16x16x32_bf16 v[18:21], v[244:247], v[186:189], v[18:21]
	v_mfma_f32_16x16x32_bf16 v[6:9], v[222:225], v[214:217], v[6:9]
	v_mfma_f32_16x16x32_bf16 v[2:5], v[244:247], v[214:217], v[2:5]
	s_setprio 0
	s_add_i32 s64, s64, 2
	s_add_u32 s46, s46, 0x100
	s_addc_u32 s47, s47, 0
	s_add_u32 s48, s48, 0x100
	s_addc_u32 s49, s49, 0
	s_cmp_gt_u32 s64, 13
	s_barrier
	s_cbranch_scc0 .LBB0_48
	v_lshl_add_u32 v150, s61, 8, v146
	v_lshl_or_b32 v132, s60, 8, v148
	v_ashrrev_i32_e32 v151, 31, v150
	v_ashrrev_i32_e32 v133, 31, v132
	v_lshlrev_b64 v[152:153], 13, v[150:151]
	v_max_f32_e32 v122, v122, v122
	v_max_f32_e32 v123, v123, v123
	v_lshl_add_u64 v[152:153], s[6:7], 0, v[152:153]
	v_lshlrev_b64 v[154:155], 1, v[132:133]
	v_max_f32_e32 v122, 0, v122
	v_max_f32_e32 v123, 0, v123
	v_lshl_add_u64 v[132:133], v[152:153], 0, v[154:155]
	v_pk_mul_f32 v[152:153], v[122:123], v[122:123]
	v_max_f32_e32 v123, v124, v124
	v_max_f32_e32 v126, v126, v126
	v_max_f32_e32 v127, v127, v127
	v_max_f32_e32 v122, v128, v128
	v_max_f32_e32 v124, 0, v123
	v_max_f32_e32 v123, v129, v129
	v_max_f32_e32 v125, v125, v125
	v_max_f32_e32 v126, 0, v126
	v_max_f32_e32 v127, 0, v127
	v_max_f32_e32 v122, 0, v122
	v_max_f32_e32 v123, 0, v123
	v_max_f32_e32 v125, 0, v125
	v_pk_mul_f32 v[126:127], v[126:127], v[126:127]
	v_pk_mul_f32 v[128:129], v[122:123], v[122:123]
	v_pk_mul_f32 v[156:157], v[124:125], v[124:125]
	v_max_f32_e32 v114, v114, v114
	v_max_f32_e32 v115, v115, v115
	v_cvt_pk_bf16_f32 v122, v126, v127
	v_cvt_pk_bf16_f32 v123, v128, v129
	v_cvt_pk_bf16_f32 v124, v152, v153
	v_cvt_pk_bf16_f32 v125, v156, v157
	v_max_f32_e32 v114, 0, v114
	v_max_f32_e32 v115, 0, v115
	global_store_dwordx4 v[132:133], v[122:125], off nt
	v_max_f32_e32 v118, v118, v118
	v_max_f32_e32 v119, v119, v119
	v_pk_mul_f32 v[122:123], v[114:115], v[114:115]
	v_max_f32_e32 v115, v116, v116
	v_max_f32_e32 v114, v120, v120
	v_max_f32_e32 v116, 0, v115
	v_max_f32_e32 v115, v121, v121
	v_max_f32_e32 v117, v117, v117
	v_max_f32_e32 v118, 0, v118
	v_max_f32_e32 v119, 0, v119
	v_max_f32_e32 v114, 0, v114
	v_max_f32_e32 v115, 0, v115
	v_max_f32_e32 v117, 0, v117
	v_pk_mul_f32 v[118:119], v[118:119], v[118:119]
	v_pk_mul_f32 v[120:121], v[114:115], v[114:115]
	v_pk_mul_f32 v[124:125], v[116:117], v[116:117]
	v_max_f32_e32 v106, v106, v106
	v_max_f32_e32 v107, v107, v107
	v_cvt_pk_bf16_f32 v114, v118, v119
	v_cvt_pk_bf16_f32 v115, v120, v121
	v_cvt_pk_bf16_f32 v116, v122, v123
	v_cvt_pk_bf16_f32 v117, v124, v125
	v_max_f32_e32 v106, 0, v106
	v_max_f32_e32 v107, 0, v107
	global_store_dwordx4 v[132:133], v[114:117], off offset:256 nt
	v_max_f32_e32 v110, v110, v110
	v_max_f32_e32 v111, v111, v111
	v_or_b32_e32 v114, 16, v150
	v_pk_mul_f32 v[116:117], v[106:107], v[106:107]
	v_max_f32_e32 v107, v108, v108
	v_ashrrev_i32_e32 v115, 31, v114
	v_max_f32_e32 v106, v112, v112
	v_max_f32_e32 v108, 0, v107
	v_max_f32_e32 v107, v113, v113
	v_max_f32_e32 v109, v109, v109
	v_lshlrev_b64 v[114:115], 13, v[114:115]
	v_max_f32_e32 v110, 0, v110
	v_max_f32_e32 v111, 0, v111
	v_max_f32_e32 v106, 0, v106
	v_max_f32_e32 v107, 0, v107
	v_max_f32_e32 v109, 0, v109
	v_lshl_add_u64 v[114:115], s[6:7], 0, v[114:115]
	v_pk_mul_f32 v[110:111], v[110:111], v[110:111]
; DI unsigned pk2(float lo, float hi) { f32x2 v = {lo, hi}; bf2_t b = __builtin_convertvector(v, bf2_t); return __builtin_bit_cast(unsigned, b); }
;     DI void operator()(const f32x4 (&acc)[2][2][4][2], const Unit& u, int wr, int wc, int fr, int fq) const {
;     ...
;         for (int ai = 0; ai < 2; ++ai)
; #pragma unroll
;             for (int m = 0; m < 4; ++m) { bf16_t* rowp = O + (size_t)(row0 + ai * HALF + m * 16) * ldc + col0;
; #pragma unroll
;                 for (int bj = 0; bj < 2; ++bj) { f32x4 v0 = acc[ai][bj][m][0], v1 = acc[ai][bj][m][1];
;                     if (ACT == 1) {
; #pragma unroll
;                         for (int j = 0; j < 4; ++j) { float a = fmaxf(v0[j], 0.f), b = fmaxf(v1[j], 0.f); v0[j] = a * a; v1[j] = b * b; } }
;                     u32x4 w; w.x = pk2(v0[0], v0[1]); w.y = pk2(v0[2], v0[3]); w.z = pk2(v1[0], v1[1]); w.w = pk2(v1[2], v1[3]);
;                     *(u32x4*)(rowp + bj * HALF) = w; } }
	v_pk_mul_f32 v[112:113], v[106:107], v[106:107]
	v_pk_mul_f32 v[118:119], v[108:109], v[108:109]
	v_max_f32_e32 v98, v98, v98
	v_max_f32_e32 v99, v99, v99
	v_lshl_add_u64 v[114:115], v[114:115], 0, v[154:155]
	v_cvt_pk_bf16_f32 v106, v110, v111
	v_cvt_pk_bf16_f32 v107, v112, v113
	v_cvt_pk_bf16_f32 v108, v116, v117
	v_cvt_pk_bf16_f32 v109, v118, v119
	v_max_f32_e32 v98, 0, v98
	v_max_f32_e32 v99, 0, v99
	global_store_dwordx4 v[114:115], v[106:109], off nt
	v_max_f32_e32 v102, v102, v102
	v_max_f32_e32 v103, v103, v103
	v_pk_mul_f32 v[106:107], v[98:99], v[98:99]
	v_max_f32_e32 v99, v100, v100
	v_max_f32_e32 v98, v104, v104
	v_max_f32_e32 v100, 0, v99
	v_max_f32_e32 v99, v105, v105
	v_max_f32_e32 v101, v101, v101
	v_max_f32_e32 v102, 0, v102
	v_max_f32_e32 v103, 0, v103
	v_max_f32_e32 v98, 0, v98
	v_max_f32_e32 v99, 0, v99
	v_max_f32_e32 v101, 0, v101
	v_pk_mul_f32 v[102:103], v[102:103], v[102:103]
	v_pk_mul_f32 v[104:105], v[98:99], v[98:99]
	v_pk_mul_f32 v[108:109], v[100:101], v[100:101]
	v_max_f32_e32 v90, v90, v90
	v_max_f32_e32 v91, v91, v91
	v_cvt_pk_bf16_f32 v98, v102, v103
	v_cvt_pk_bf16_f32 v99, v104, v105
	v_cvt_pk_bf16_f32 v100, v106, v107
	v_cvt_pk_bf16_f32 v101, v108, v109
	v_max_f32_e32 v90, 0, v90
	v_max_f32_e32 v91, 0, v91
	global_store_dwordx4 v[114:115], v[98:101], off offset:256 nt
	v_max_f32_e32 v94, v94, v94
	v_max_f32_e32 v95, v95, v95
	v_or_b32_e32 v98, 32, v150
	v_pk_mul_f32 v[100:101], v[90:91], v[90:91]
	v_max_f32_e32 v91, v92, v92
	v_ashrrev_i32_e32 v99, 31, v98
	v_max_f32_e32 v90, v96, v96
	v_max_f32_e32 v92, 0, v91
	v_max_f32_e32 v91, v97, v97
	v_max_f32_e32 v93, v93, v93
	v_lshlrev_b64 v[98:99], 13, v[98:99]
	v_max_f32_e32 v94, 0, v94
	v_max_f32_e32 v95, 0, v95
	v_max_f32_e32 v90, 0, v90
	v_max_f32_e32 v91, 0, v91
	v_max_f32_e32 v93, 0, v93
	v_lshl_add_u64 v[98:99], s[6:7], 0, v[98:99]
	v_pk_mul_f32 v[94:95], v[94:95], v[94:95]
	v_pk_mul_f32 v[96:97], v[90:91], v[90:91]
	v_pk_mul_f32 v[102:103], v[92:93], v[92:93]
	v_max_f32_e32 v82, v82, v82
	v_max_f32_e32 v83, v83, v83
	v_lshl_add_u64 v[98:99], v[98:99], 0, v[154:155]
	v_cvt_pk_bf16_f32 v90, v94, v95
	v_cvt_pk_bf16_f32 v91, v96, v97
	v_cvt_pk_bf16_f32 v92, v100, v101
	v_cvt_pk_bf16_f32 v93, v102, v103
	v_max_f32_e32 v82, 0, v82
	v_max_f32_e32 v83, 0, v83
	global_store_dwordx4 v[98:99], v[90:93], off nt
	v_max_f32_e32 v86, v86, v86
	v_max_f32_e32 v87, v87, v87
	v_pk_mul_f32 v[90:91], v[82:83], v[82:83]
	v_max_f32_e32 v83, v84, v84
	v_max_f32_e32 v82, v88, v88
	v_max_f32_e32 v84, 0, v83
	v_max_f32_e32 v83, v89, v89
	v_max_f32_e32 v85, v85, v85
	v_max_f32_e32 v86, 0, v86
	v_max_f32_e32 v87, 0, v87
	v_max_f32_e32 v82, 0, v82
	v_max_f32_e32 v83, 0, v83
	v_max_f32_e32 v85, 0, v85
	v_pk_mul_f32 v[86:87], v[86:87], v[86:87]
	v_pk_mul_f32 v[88:89], v[82:83], v[82:83]
	v_pk_mul_f32 v[92:93], v[84:85], v[84:85]
	v_max_f32_e32 v74, v74, v74
	v_max_f32_e32 v75, v75, v75
	v_cvt_pk_bf16_f32 v82, v86, v87
	v_cvt_pk_bf16_f32 v83, v88, v89
	v_cvt_pk_bf16_f32 v84, v90, v91
	v_cvt_pk_bf16_f32 v85, v92, v93
	v_max_f32_e32 v74, 0, v74
	v_max_f32_e32 v75, 0, v75
	global_store_dwordx4 v[98:99], v[82:85], off offset:256 nt
	v_max_f32_e32 v78, v78, v78
	v_max_f32_e32 v79, v79, v79
	v_or_b32_e32 v82, 48, v150
	v_pk_mul_f32 v[84:85], v[74:75], v[74:75]
	v_max_f32_e32 v75, v76, v76
	v_ashrrev_i32_e32 v83, 31, v82
	v_max_f32_e32 v74, v80, v80
	v_max_f32_e32 v76, 0, v75
	v_max_f32_e32 v75, v81, v81
	v_max_f32_e32 v77, v77, v77
	v_lshlrev_b64 v[82:83], 13, v[82:83]
	v_max_f32_e32 v78, 0, v78
	v_max_f32_e32 v79, 0, v79
	v_max_f32_e32 v74, 0, v74
	v_max_f32_e32 v75, 0, v75
	v_max_f32_e32 v77, 0, v77
	v_lshl_add_u64 v[82:83], s[6:7], 0, v[82:83]
	v_pk_mul_f32 v[78:79], v[78:79], v[78:79]
	v_pk_mul_f32 v[80:81], v[74:75], v[74:75]
	v_pk_mul_f32 v[86:87], v[76:77], v[76:77]
	v_max_f32_e32 v66, v66, v66
	v_max_f32_e32 v67, v67, v67
	v_lshl_add_u64 v[82:83], v[82:83], 0, v[154:155]
	v_cvt_pk_bf16_f32 v74, v78, v79
	v_cvt_pk_bf16_f32 v75, v80, v81
	v_cvt_pk_bf16_f32 v76, v84, v85
	v_cvt_pk_bf16_f32 v77, v86, v87
	v_max_f32_e32 v66, 0, v66
	v_max_f32_e32 v67, 0, v67
	global_store_dwordx4 v[82:83], v[74:77], off nt
	v_max_f32_e32 v70, v70, v70
	v_max_f32_e32 v71, v71, v71
	v_pk_mul_f32 v[74:75], v[66:67], v[66:67]
	v_max_f32_e32 v67, v68, v68
	v_max_f32_e32 v66, v72, v72
	v_max_f32_e32 v68, 0, v67
	v_max_f32_e32 v67, v73, v73
	v_max_f32_e32 v69, v69, v69
	v_max_f32_e32 v70, 0, v70
	v_max_f32_e32 v71, 0, v71
	v_max_f32_e32 v66, 0, v66
	v_max_f32_e32 v67, 0, v67
	v_max_f32_e32 v69, 0, v69
	v_pk_mul_f32 v[70:71], v[70:71], v[70:71]
	v_pk_mul_f32 v[72:73], v[66:67], v[66:67]
	v_pk_mul_f32 v[76:77], v[68:69], v[68:69]
	v_max_f32_e32 v58, v58, v58
	v_max_f32_e32 v59, v59, v59
	v_cvt_pk_bf16_f32 v66, v70, v71
	v_cvt_pk_bf16_f32 v67, v72, v73
	v_cvt_pk_bf16_f32 v68, v74, v75
	v_cvt_pk_bf16_f32 v69, v76, v77
	v_max_f32_e32 v58, 0, v58
	v_max_f32_e32 v59, 0, v59
	global_store_dwordx4 v[82:83], v[66:69], off offset:256 nt
	v_max_f32_e32 v62, v62, v62
	v_max_f32_e32 v63, v63, v63
	v_pk_mul_f32 v[68:69], v[58:59], v[58:59]
	v_max_f32_e32 v59, v60, v60
	v_max_f32_e32 v62, 0, v62
	v_max_f32_e32 v63, 0, v63
	v_max_f32_e32 v58, v64, v64
	v_max_f32_e32 v60, 0, v59
	v_max_f32_e32 v59, v65, v65
	v_max_f32_e32 v61, v61, v61
	v_pk_mul_f32 v[62:63], v[62:63], v[62:63]
	v_max_f32_e32 v58, 0, v58
	v_max_f32_e32 v59, 0, v59
	v_max_f32_e32 v61, 0, v61
	s_mov_b32 s5, 0x100000
	v_pk_mul_f32 v[64:65], v[58:59], v[58:59]
	v_pk_mul_f32 v[70:71], v[60:61], v[60:61]
	v_cvt_pk_bf16_f32 v58, v62, v63
	v_add_co_u32_e32 v62, vcc, s5, v132
	v_max_f32_e32 v50, v50, v50
	v_max_f32_e32 v51, v51, v51
	v_cvt_pk_bf16_f32 v59, v64, v65
; DI unsigned pk2(float lo, float hi) { f32x2 v = {lo, hi}; bf2_t b = __builtin_convertvector(v, bf2_t); return __builtin_bit_cast(unsigned, b); }
;     DI void operator()(const f32x4 (&acc)[2][2][4][2], const Unit& u, int wr, int wc, int fr, int fq) const {
;     ...
;         for (int ai = 0; ai < 2; ++ai)
; #pragma unroll
;             for (int m = 0; m < 4; ++m) { bf16_t* rowp = O + (size_t)(row0 + ai * HALF + m * 16) * ldc + col0;
; #pragma unroll
;                 for (int bj = 0; bj < 2; ++bj) { f32x4 v0 = acc[ai][bj][m][0], v1 = acc[ai][bj][m][1];
;                     if (ACT == 1) {
; #pragma unroll
;                         for (int j = 0; j < 4; ++j) { float a = fmaxf(v0[j], 0.f), b = fmaxf(v1[j], 0.f); v0[j] = a * a; v1[j] = b * b; } }
;                     u32x4 w; w.x = pk2(v0[0], v0[1]); w.y = pk2(v0[2], v0[3]); w.z = pk2(v1[0], v1[1]); w.w = pk2(v1[2], v1[3]);
;                     *(u32x4*)(rowp + bj * HALF) = w; } }
; template <class Epi, class Sched>
; DI void gemm_phase(LAS unsigned char* lds, const Gemm g, const Sched& S, const Epi& E, const int tid) {
;     ...
;         E(acc, cur, wr, wc, fr, fq);
;         if (!has_next) break;
; #pragma unroll
;         for (int a = 0; a < 2; ++a)
; #pragma unroll
;             for (int b = 0; b < 2; ++b)
; #pragma unroll
;                 for (int m = 0; m < 4; ++m)
; #pragma unroll
;                     for (int n = 0; n < 2; ++n) acc[a][b][m][n] = (f32x4){0.f, 0.f, 0.f, 0.f};
;         cur = nxt; cA = nA; cB = nB; ++ui;
	v_cvt_pk_bf16_f32 v60, v68, v69
	v_cvt_pk_bf16_f32 v61, v70, v71
	v_addc_co_u32_e32 v63, vcc, 0, v133, vcc
	v_max_f32_e32 v50, 0, v50
	v_max_f32_e32 v51, 0, v51
	global_store_dwordx4 v[62:63], v[58:61], off nt
	v_max_f32_e32 v54, v54, v54
	v_max_f32_e32 v55, v55, v55
	v_pk_mul_f32 v[58:59], v[50:51], v[50:51]
	v_max_f32_e32 v51, v52, v52
	v_max_f32_e32 v50, v56, v56
	v_max_f32_e32 v52, 0, v51
	v_max_f32_e32 v51, v57, v57
	v_max_f32_e32 v53, v53, v53
	v_max_f32_e32 v54, 0, v54
	v_max_f32_e32 v55, 0, v55
	v_max_f32_e32 v50, 0, v50
	v_max_f32_e32 v51, 0, v51
	v_max_f32_e32 v53, 0, v53
	s_mov_b64 s[46:47], 0x100000
	v_pk_mul_f32 v[54:55], v[54:55], v[54:55]
	v_pk_mul_f32 v[56:57], v[50:51], v[50:51]
	v_pk_mul_f32 v[60:61], v[52:53], v[52:53]
	v_max_f32_e32 v42, v42, v42
	v_max_f32_e32 v43, v43, v43
	v_lshl_add_u64 v[66:67], v[132:133], 0, s[46:47]
	v_cvt_pk_bf16_f32 v50, v54, v55
	v_cvt_pk_bf16_f32 v51, v56, v57
	v_cvt_pk_bf16_f32 v52, v58, v59
	v_cvt_pk_bf16_f32 v53, v60, v61
	v_max_f32_e32 v42, 0, v42
	v_max_f32_e32 v43, 0, v43
	global_store_dwordx4 v[66:67], v[50:53], off offset:256 nt
	v_max_f32_e32 v46, v46, v46
	v_max_f32_e32 v47, v47, v47
	v_pk_mul_f32 v[52:53], v[42:43], v[42:43]
	v_max_f32_e32 v43, v44, v44
	v_max_f32_e32 v46, 0, v46
	v_max_f32_e32 v47, 0, v47
	v_max_f32_e32 v42, v48, v48
	v_max_f32_e32 v44, 0, v43
	v_max_f32_e32 v43, v49, v49
	v_max_f32_e32 v45, v45, v45
	v_pk_mul_f32 v[46:47], v[46:47], v[46:47]
	v_max_f32_e32 v42, 0, v42
	v_max_f32_e32 v43, 0, v43
	v_max_f32_e32 v45, 0, v45
	s_mov_b32 s5, 0x120000
	v_pk_mul_f32 v[48:49], v[42:43], v[42:43]
	v_pk_mul_f32 v[54:55], v[44:45], v[44:45]
	v_cvt_pk_bf16_f32 v42, v46, v47
	v_add_co_u32_e32 v46, vcc, s5, v132
	v_max_f32_e32 v34, v34, v34
	v_max_f32_e32 v35, v35, v35
	v_cvt_pk_bf16_f32 v43, v48, v49
	v_cvt_pk_bf16_f32 v44, v52, v53
	v_cvt_pk_bf16_f32 v45, v54, v55
	v_addc_co_u32_e32 v47, vcc, 0, v133, vcc
	v_max_f32_e32 v34, 0, v34
	v_max_f32_e32 v35, 0, v35
	global_store_dwordx4 v[46:47], v[42:45], off nt
	v_max_f32_e32 v38, v38, v38
	v_max_f32_e32 v39, v39, v39
	v_pk_mul_f32 v[42:43], v[34:35], v[34:35]
	v_max_f32_e32 v35, v36, v36
	v_max_f32_e32 v34, v40, v40
	v_max_f32_e32 v36, 0, v35
	v_max_f32_e32 v35, v41, v41
	v_max_f32_e32 v37, v37, v37
	v_max_f32_e32 v38, 0, v38
	v_max_f32_e32 v39, 0, v39
	v_max_f32_e32 v34, 0, v34
	v_max_f32_e32 v35, 0, v35
	v_max_f32_e32 v37, 0, v37
	s_mov_b64 s[46:47], 0x120000
	v_pk_mul_f32 v[38:39], v[38:39], v[38:39]
	v_pk_mul_f32 v[40:41], v[34:35], v[34:35]
	v_pk_mul_f32 v[44:45], v[36:37], v[36:37]
	v_max_f32_e32 v26, v26, v26
	v_max_f32_e32 v27, v27, v27
	v_lshl_add_u64 v[50:51], v[132:133], 0, s[46:47]
	v_cvt_pk_bf16_f32 v34, v38, v39
	v_cvt_pk_bf16_f32 v35, v40, v41
	v_cvt_pk_bf16_f32 v36, v42, v43
	v_cvt_pk_bf16_f32 v37, v44, v45
	v_max_f32_e32 v26, 0, v26
	v_max_f32_e32 v27, 0, v27
	global_store_dwordx4 v[50:51], v[34:37], off offset:256 nt
	v_max_f32_e32 v30, v30, v30
	v_max_f32_e32 v31, v31, v31
	v_pk_mul_f32 v[36:37], v[26:27], v[26:27]
	v_max_f32_e32 v27, v28, v28
	v_max_f32_e32 v30, 0, v30
	v_max_f32_e32 v31, 0, v31
	v_max_f32_e32 v26, v32, v32
	v_max_f32_e32 v28, 0, v27
	v_max_f32_e32 v27, v33, v33
	v_max_f32_e32 v29, v29, v29
	v_pk_mul_f32 v[30:31], v[30:31], v[30:31]
	v_max_f32_e32 v26, 0, v26
	v_max_f32_e32 v27, 0, v27
	v_max_f32_e32 v29, 0, v29
	s_mov_b32 s5, 0x140000
	v_pk_mul_f32 v[32:33], v[26:27], v[26:27]
	v_pk_mul_f32 v[38:39], v[28:29], v[28:29]
	v_cvt_pk_bf16_f32 v26, v30, v31
	v_add_co_u32_e32 v30, vcc, s5, v132
	v_max_f32_e32 v18, v18, v18
	v_max_f32_e32 v19, v19, v19
	v_cvt_pk_bf16_f32 v27, v32, v33
	v_cvt_pk_bf16_f32 v28, v36, v37
	v_cvt_pk_bf16_f32 v29, v38, v39
	v_addc_co_u32_e32 v31, vcc, 0, v133, vcc
	v_max_f32_e32 v18, 0, v18
	v_max_f32_e32 v19, 0, v19
	global_store_dwordx4 v[30:31], v[26:29], off nt
	v_max_f32_e32 v22, v22, v22
	v_max_f32_e32 v23, v23, v23
	v_pk_mul_f32 v[26:27], v[18:19], v[18:19]
	v_max_f32_e32 v19, v20, v20
	v_max_f32_e32 v18, v24, v24
	v_max_f32_e32 v20, 0, v19
	v_max_f32_e32 v19, v25, v25
	v_max_f32_e32 v21, v21, v21
	v_max_f32_e32 v22, 0, v22
	v_max_f32_e32 v23, 0, v23
	v_max_f32_e32 v18, 0, v18
	v_max_f32_e32 v19, 0, v19
	v_max_f32_e32 v21, 0, v21
	s_mov_b64 s[46:47], 0x140000
	v_pk_mul_f32 v[22:23], v[22:23], v[22:23]
	v_pk_mul_f32 v[24:25], v[18:19], v[18:19]
	v_pk_mul_f32 v[28:29], v[20:21], v[20:21]
	v_max_f32_e32 v10, v10, v10
	v_max_f32_e32 v11, v11, v11
	v_lshl_add_u64 v[34:35], v[132:133], 0, s[46:47]
	v_cvt_pk_bf16_f32 v18, v22, v23
	v_cvt_pk_bf16_f32 v19, v24, v25
	v_cvt_pk_bf16_f32 v20, v26, v27
	v_cvt_pk_bf16_f32 v21, v28, v29
	v_max_f32_e32 v10, 0, v10
	v_max_f32_e32 v11, 0, v11
	global_store_dwordx4 v[34:35], v[18:21], off offset:256 nt
	v_max_f32_e32 v14, v14, v14
	v_max_f32_e32 v15, v15, v15
	v_pk_mul_f32 v[20:21], v[10:11], v[10:11]
	v_max_f32_e32 v11, v12, v12
	v_max_f32_e32 v14, 0, v14
	v_max_f32_e32 v15, 0, v15
	v_max_f32_e32 v10, v16, v16
	v_max_f32_e32 v12, 0, v11
	v_max_f32_e32 v11, v17, v17
	v_max_f32_e32 v13, v13, v13
	v_pk_mul_f32 v[14:15], v[14:15], v[14:15]
	v_max_f32_e32 v10, 0, v10
	v_max_f32_e32 v11, 0, v11
	v_max_f32_e32 v13, 0, v13
	s_mov_b32 s5, 0x160000
	v_pk_mul_f32 v[16:17], v[10:11], v[10:11]
	v_pk_mul_f32 v[22:23], v[12:13], v[12:13]
	v_cvt_pk_bf16_f32 v10, v14, v15
	v_add_co_u32_e32 v14, vcc, s5, v132
	v_max_f32_e32 v2, v2, v2
	v_max_f32_e32 v3, v3, v3
	v_cvt_pk_bf16_f32 v11, v16, v17
	v_cvt_pk_bf16_f32 v12, v20, v21
	v_cvt_pk_bf16_f32 v13, v22, v23
	v_addc_co_u32_e32 v15, vcc, 0, v133, vcc
	v_max_f32_e32 v2, 0, v2
	v_max_f32_e32 v3, 0, v3
	global_store_dwordx4 v[14:15], v[10:13], off nt
	v_max_f32_e32 v6, v6, v6
	v_max_f32_e32 v7, v7, v7
	v_pk_mul_f32 v[10:11], v[2:3], v[2:3]
	v_max_f32_e32 v3, v4, v4
	v_max_f32_e32 v2, v8, v8
	v_max_f32_e32 v4, 0, v3
	v_max_f32_e32 v3, v9, v9
	v_max_f32_e32 v5, v5, v5
	v_max_f32_e32 v6, 0, v6
	v_max_f32_e32 v7, 0, v7
	v_max_f32_e32 v2, 0, v2
	v_max_f32_e32 v3, 0, v3
	v_max_f32_e32 v5, 0, v5
	s_mov_b64 s[46:47], 0x160000
	v_pk_mul_f32 v[6:7], v[6:7], v[6:7]
	v_pk_mul_f32 v[8:9], v[2:3], v[2:3]
	v_pk_mul_f32 v[12:13], v[4:5], v[4:5]
	v_lshl_add_u64 v[18:19], v[132:133], 0, s[46:47]
	v_cvt_pk_bf16_f32 v2, v6, v7
	v_cvt_pk_bf16_f32 v3, v8, v9
	v_cvt_pk_bf16_f32 v4, v10, v11
	v_cvt_pk_bf16_f32 v5, v12, v13
	s_and_b64 vcc, exec, s[38:39]
	s_mov_b32 s60, s4
	s_mov_b32 s61, s40
	s_mov_b64 s[48:49], s[44:45]
	s_mov_b64 s[46:47], s[42:43]
	global_store_dwordx4 v[18:19], v[2:5], off offset:256 nt
	s_cbranch_vccz .LBB0_41
	s_waitcnt vmcnt(0)
	v_readlane_b32 s60, v254, 63
	s_cmpk_gt_u32 s2, 0xff
	v_readlane_b32 s61, v255, 0
	v_readlane_b32 s62, v255, 1
	v_readlane_b32 s63, v255, 2
	v_readlane_b32 s64, v255, 3
	v_readlane_b32 s65, v255, 4
	v_readlane_b32 s66, v255, 5
	v_readlane_b32 s67, v255, 6
	v_readlane_b32 s68, v255, 7
	v_readlane_b32 s69, v255, 8
	v_readlane_b32 s70, v255, 9
	v_readlane_b32 s71, v255, 10
	v_readlane_b32 s72, v255, 11
	v_readlane_b32 s73, v255, 12
	v_readlane_b32 s74, v255, 13
	v_readlane_b32 s75, v255, 14
	s_mov_b64 s[8:9], 0
	s_cbranch_scc1 .LBB0_52
	s_barrier

; #define PG8_STAGE(bufoff, gbase, voff) do { _Pragma("unroll") for (int _i = 0; _i < 2; ++_i) \
;         __builtin_amdgcn_global_load_lds((const unsigned*)((const char*)(gbase) + (size_t)_i * p64##voff + (v##voff##_)), (LAS unsigned*)(lds + (bufoff) + ldsw + _i * 8192), 16, 0, 0); } while (0)
; #define PG8_LDA(dst, b, h) do { _Pragma("unroll") for (int m = 0; m < 4; ++m) _Pragma("unroll") for (int k = 0; k < 2; ++k) dst[m][k] = *(const LAS bf16x8*)(lds + PG8_SA(b, h) + aoff + m * 2048 + k * 1024); } while (0)
; #define PG8_LDB(dst, b, h) do { _Pragma("unroll") for (int n = 0; n < 2; ++n) _Pragma("unroll") for (int k = 0; k < 2; ++k) dst[n][k] = *(const LAS bf16x8*)(lds + PG8_SB(b, h) + boff + n * 2048 + k * 1024); } while (0)
; #define PG8_MMA(ai, bj, At, Bt) do { __builtin_amdgcn_s_setprio(1); _Pragma("unroll") for (int m = 0; m < 4; ++m) _Pragma("unroll") for (int n = 0; n < 2; ++n) _Pragma("unroll") for (int k = 0; k < 2; ++k) \
;         acc[ai][bj][m][n] = __builtin_amdgcn_mfma_f32_16x16x32_bf16(Bt[n][k], At[m][k], acc[ai][bj][m][n], 0, 0, 0); __builtin_amdgcn_s_setprio(0); } while (0)
; #define PG8_WAIT_V(n) asm volatile("s_waitcnt vmcnt(" #n ")" ::: "memory")
; #define PG8_WAIT_L(n) asm volatile("s_waitcnt lgkmcnt(" #n ")" ::: "memory")
; #define PG8_BAR __builtin_amdgcn_s_barrier()
; #define PG8_SCHED __builtin_amdgcn_sched_barrier(0)
; template <class Epi, class Sched>
; DI void gemm_phase(LAS unsigned char* lds, const Gemm g, const Sched& S, const Epi& E, const int tid) {
;     ...
;             PG8_LDB(B0, 0, 0); PG8_SCHED; PG8_LDA(At, 0, 0); PG8_STAGE(PG8_SA(1, 1), a1 + hstepA, offA);
;             PG8_WAIT_L(8); PG8_BAR; PG8_WAIT_L(0); PG8_MMA(0, 0, At, B0); PG8_BAR; PG8_SCHED;
;             PG8_LDB(B1, 0, 1); PG8_STAGE(PG8_SB(0, 0), b2, offB);
;             PG8_BAR; PG8_WAIT_L(0); PG8_MMA(0, 1, At, B1); PG8_BAR;
;             PG8_LDA(At, 0, 1); PG8_STAGE(PG8_SA(0, 0), a2, offA);
;             PG8_BAR; PG8_WAIT_L(0); PG8_MMA(1, 0, At, B0); PG8_BAR; PG8_SCHED;
;             PG8_STAGE(PG8_SB(0, 1), b2 + hstepB, offB);
;             PG8_WAIT_V(6); PG8_BAR; PG8_MMA(1, 1, At, B1); PG8_BAR;
.LBB0_146:
	s_add_u32 s45, s0, 0xfffc0080
	s_addc_u32 s60, s1, -1
	s_add_i32 s64, 0, 0x10000
	v_add_u32_e32 v149, s64, v146
	ds_read_b128 v[150:153], v149
	ds_read_b128 v[154:157], v149 offset:1024
	ds_read_b128 v[158:161], v149 offset:2048
	ds_read_b128 v[162:165], v149 offset:3072
	s_cmp_eq_u32 s44, 2
	s_cselect_b32 s61, s5, s60
	s_cselect_b32 s60, s59, s45
	s_cselect_b32 s63, s7, s43
	s_cselect_b32 s62, s6, s42
	v_lshl_add_u64 v[198:199], s[0:1], 0, v[130:131]
	s_add_i32 m0, s49, 0xc000
	ds_read_b128 v[166:169], v148
	ds_read_b128 v[170:173], v148 offset:1024
	ds_read_b128 v[174:177], v148 offset:2048
	ds_read_b128 v[178:181], v148 offset:3072
	ds_read_b128 v[182:185], v148 offset:4096
	ds_read_b128 v[186:189], v148 offset:5120
	ds_read_b128 v[190:193], v148 offset:6144
	ds_read_b128 v[214:217], v148 offset:7168
	global_load_lds_dwordx4 v[198:199], off
	v_lshl_add_u64 v[198:199], v[198:199], 0, s[10:11]
	s_add_i32 m0, s49, 0xe000
	s_nop 0
	global_load_lds_dwordx4 v[198:199], off
	s_waitcnt lgkmcnt(8)
	s_barrier
	s_waitcnt lgkmcnt(0)
	s_setprio 1
	s_waitcnt lgkmcnt(0)
	v_mfma_f32_16x16x32_bf16 v[126:129], v[150:153], v[166:169], v[126:129]
	v_mfma_f32_16x16x32_bf16 v[122:125], v[158:161], v[166:169], v[122:125]
	v_mfma_f32_16x16x32_bf16 v[118:121], v[150:153], v[174:177], v[118:121]
	v_mfma_f32_16x16x32_bf16 v[114:117], v[158:161], v[174:177], v[114:117]
	v_mfma_f32_16x16x32_bf16 v[102:105], v[150:153], v[182:185], v[102:105]
	v_mfma_f32_16x16x32_bf16 v[98:101], v[158:161], v[182:185], v[98:101]
	v_mfma_f32_16x16x32_bf16 v[86:89], v[150:153], v[190:193], v[86:89]
	v_mfma_f32_16x16x32_bf16 v[82:85], v[158:161], v[190:193], v[82:85]
	v_mfma_f32_16x16x32_bf16 v[126:129], v[154:157], v[170:173], v[126:129]
	v_mfma_f32_16x16x32_bf16 v[122:125], v[162:165], v[170:173], v[122:125]
	v_mfma_f32_16x16x32_bf16 v[118:121], v[154:157], v[178:181], v[118:121]
	v_mfma_f32_16x16x32_bf16 v[114:117], v[162:165], v[178:181], v[114:117]
	v_mfma_f32_16x16x32_bf16 v[102:105], v[154:157], v[186:189], v[102:105]
	v_mfma_f32_16x16x32_bf16 v[98:101], v[162:165], v[186:189], v[98:101]
	v_mfma_f32_16x16x32_bf16 v[86:89], v[154:157], v[214:217], v[86:89]
	v_mfma_f32_16x16x32_bf16 v[82:85], v[162:165], v[214:217], v[82:85]
	s_setprio 0
	s_barrier
	s_add_i32 s45, 0, 0x14000
	v_lshl_add_u64 v[198:199], s[62:63], 0, v[0:1]
	s_add_i32 s62, s64, s48
	v_add_u32_e32 v149, s45, v146
	s_mov_b32 m0, s62
	ds_read_b128 v[218:221], v149
	ds_read_b128 v[222:225], v149 offset:1024
	ds_read_b128 v[226:229], v149 offset:2048
	ds_read_b128 v[244:247], v149 offset:3072
	global_load_lds_dwordx4 v[198:199], off
	v_lshl_add_u64 v[200:201], v[198:199], 0, s[68:69]
	s_add_i32 m0, s62, 0x2000
	s_nop 0
	global_load_lds_dwordx4 v[200:201], off
	s_barrier
	s_waitcnt lgkmcnt(0)
	s_setprio 1
	s_waitcnt lgkmcnt(0)
	v_mfma_f32_16x16x32_bf16 v[110:113], v[218:221], v[166:169], v[110:113]
	v_mfma_f32_16x16x32_bf16 v[106:109], v[226:229], v[166:169], v[106:109]
	v_mfma_f32_16x16x32_bf16 v[94:97], v[218:221], v[174:177], v[94:97]
	v_mfma_f32_16x16x32_bf16 v[90:93], v[226:229], v[174:177], v[90:93]
	v_mfma_f32_16x16x32_bf16 v[78:81], v[218:221], v[182:185], v[78:81]
	v_mfma_f32_16x16x32_bf16 v[74:77], v[226:229], v[182:185], v[74:77]
	v_mfma_f32_16x16x32_bf16 v[70:73], v[218:221], v[190:193], v[70:73]
	v_mfma_f32_16x16x32_bf16 v[66:69], v[226:229], v[190:193], v[66:69]
	v_mfma_f32_16x16x32_bf16 v[110:113], v[222:225], v[170:173], v[110:113]
	v_mfma_f32_16x16x32_bf16 v[106:109], v[244:247], v[170:173], v[106:109]
	v_mfma_f32_16x16x32_bf16 v[94:97], v[222:225], v[178:181], v[94:97]
	v_mfma_f32_16x16x32_bf16 v[90:93], v[244:247], v[178:181], v[90:93]
	v_mfma_f32_16x16x32_bf16 v[78:81], v[222:225], v[186:189], v[78:81]
	v_mfma_f32_16x16x32_bf16 v[74:77], v[244:247], v[186:189], v[74:77]
	v_mfma_f32_16x16x32_bf16 v[70:73], v[222:225], v[214:217], v[70:73]
	v_mfma_f32_16x16x32_bf16 v[66:69], v[244:247], v[214:217], v[66:69]
	s_setprio 0
	s_mov_b32 m0, s49
	v_lshl_add_u64 v[200:201], s[60:61], 0, v[212:213]
	s_barrier
	ds_read_b128 v[166:169], v148 offset:16384
	ds_read_b128 v[170:173], v148 offset:17408
	ds_read_b128 v[174:177], v148 offset:18432
	ds_read_b128 v[178:181], v148 offset:19456
	ds_read_b128 v[182:185], v148 offset:20480
	ds_read_b128 v[186:189], v148 offset:21504
	ds_read_b128 v[190:193], v148 offset:22528
	ds_read_b128 v[214:217], v148 offset:23552
	global_load_lds_dwordx4 v[200:201], off
	v_lshl_add_u64 v[230:231], v[200:201], 0, s[10:11]
	s_mov_b32 m0, s50
	s_nop 0
	global_load_lds_dwordx4 v[230:231], off
	s_barrier
	s_waitcnt lgkmcnt(0)
	s_setprio 1
	s_waitcnt lgkmcnt(0)
	v_mfma_f32_16x16x32_bf16 v[62:65], v[150:153], v[166:169], v[62:65]
	v_mfma_f32_16x16x32_bf16 v[58:61], v[158:161], v[166:169], v[58:61]
	v_mfma_f32_16x16x32_bf16 v[54:57], v[150:153], v[174:177], v[54:57]
	v_mfma_f32_16x16x32_bf16 v[50:53], v[158:161], v[174:177], v[50:53]
	v_mfma_f32_16x16x32_bf16 v[38:41], v[150:153], v[182:185], v[38:41]
	v_mfma_f32_16x16x32_bf16 v[34:37], v[158:161], v[182:185], v[34:37]
	v_mfma_f32_16x16x32_bf16 v[22:25], v[150:153], v[190:193], v[22:25]
	v_mfma_f32_16x16x32_bf16 v[18:21], v[158:161], v[190:193], v[18:21]
	v_mfma_f32_16x16x32_bf16 v[62:65], v[154:157], v[170:173], v[62:65]
	v_mfma_f32_16x16x32_bf16 v[58:61], v[162:165], v[170:173], v[58:61]
	v_mfma_f32_16x16x32_bf16 v[54:57], v[154:157], v[178:181], v[54:57]
	v_mfma_f32_16x16x32_bf16 v[50:53], v[162:165], v[178:181], v[50:53]
	v_mfma_f32_16x16x32_bf16 v[38:41], v[154:157], v[186:189], v[38:41]
	v_mfma_f32_16x16x32_bf16 v[34:37], v[162:165], v[186:189], v[34:37]
	v_mfma_f32_16x16x32_bf16 v[22:25], v[154:157], v[214:217], v[22:25]
	v_mfma_f32_16x16x32_bf16 v[18:21], v[162:165], v[214:217], v[18:21]
	s_setprio 0
	s_barrier
; #define PG8_STAGE(bufoff, gbase, voff) do { _Pragma("unroll") for (int _i = 0; _i < 2; ++_i) \
;         __builtin_amdgcn_global_load_lds((const unsigned*)((const char*)(gbase) + (size_t)_i * p64##voff + (v##voff##_)), (LAS unsigned*)(lds + (bufoff) + ldsw + _i * 8192), 16, 0, 0); } while (0)
; #define PG8_LDA(dst, b, h) do { _Pragma("unroll") for (int m = 0; m < 4; ++m) _Pragma("unroll") for (int k = 0; k < 2; ++k) dst[m][k] = *(const LAS bf16x8*)(lds + PG8_SA(b, h) + aoff + m * 2048 + k * 1024); } while (0)
; #define PG8_LDB(dst, b, h) do { _Pragma("unroll") for (int n = 0; n < 2; ++n) _Pragma("unroll") for (int k = 0; k < 2; ++k) dst[n][k] = *(const LAS bf16x8*)(lds + PG8_SB(b, h) + boff + n * 2048 + k * 1024); } while (0)
; #define PG8_MMA(ai, bj, At, Bt) do { __builtin_amdgcn_s_setprio(1); _Pragma("unroll") for (int m = 0; m < 4; ++m) _Pragma("unroll") for (int n = 0; n < 2; ++n) _Pragma("unroll") for (int k = 0; k < 2; ++k) \
;         acc[ai][bj][m][n] = __builtin_amdgcn_mfma_f32_16x16x32_bf16(Bt[n][k], At[m][k], acc[ai][bj][m][n], 0, 0, 0); __builtin_amdgcn_s_setprio(0); } while (0)
; #define PG8_WAIT_V(n) asm volatile("s_waitcnt vmcnt(" #n ")" ::: "memory")
; #define PG8_WAIT_L(n) asm volatile("s_waitcnt lgkmcnt(" #n ")" ::: "memory")
; #define PG8_BAR __builtin_amdgcn_s_barrier()
; #define PG8_SCHED __builtin_amdgcn_sched_barrier(0)
; template <class Epi, class Sched>
; DI void gemm_phase(LAS unsigned char* lds, const Gemm g, const Sched& S, const Epi& E, const int tid) {
;     ...
;             PG8_STAGE(PG8_SB(0, 1), b2 + hstepB, offB);
;             PG8_WAIT_V(6); PG8_BAR; PG8_MMA(1, 1, At, B1); PG8_BAR;
;             PG8_LDB(B0, 1, 0); PG8_SCHED; PG8_LDA(At, 1, 0); PG8_STAGE(PG8_SA(0, 1), a2 + hstepA, offA);
;             PG8_WAIT_L(8); PG8_BAR; PG8_WAIT_L(0); PG8_MMA(0, 0, At, B0); PG8_BAR; PG8_SCHED;
;             PG8_LDB(B1, 1, 1); PG8_STAGE(PG8_SB(1, 0), b3, offB);
;             PG8_BAR; PG8_WAIT_L(0); PG8_MMA(0, 1, At, B1); PG8_BAR;
;             PG8_LDA(At, 1, 1); PG8_STAGE(PG8_SA(1, 0), a3, offA);
;             PG8_BAR; PG8_WAIT_L(0); PG8_MMA(1, 0, At, B0); PG8_BAR; PG8_SCHED;
	s_add_i32 s45, s45, s48
	v_lshl_add_u64 v[150:151], v[198:199], 0, s[38:39]
	s_mov_b32 m0, s45
	s_nop 0
	global_load_lds_dwordx4 v[150:151], off
	v_lshl_add_u64 v[150:151], v[198:199], 0, s[70:71]
	s_add_i32 m0, s45, 0x2000
	s_nop 0
	global_load_lds_dwordx4 v[150:151], off
	s_waitcnt vmcnt(6)
	s_barrier
	s_setprio 1
	v_mfma_f32_16x16x32_bf16 v[46:49], v[218:221], v[166:169], v[46:49]
	v_mfma_f32_16x16x32_bf16 v[42:45], v[226:229], v[166:169], v[42:45]
	v_mfma_f32_16x16x32_bf16 v[30:33], v[218:221], v[174:177], v[30:33]
	v_mfma_f32_16x16x32_bf16 v[26:29], v[226:229], v[174:177], v[26:29]
	v_mfma_f32_16x16x32_bf16 v[14:17], v[218:221], v[182:185], v[14:17]
	v_mfma_f32_16x16x32_bf16 v[10:13], v[226:229], v[182:185], v[10:13]
	v_mfma_f32_16x16x32_bf16 v[6:9], v[218:221], v[190:193], v[6:9]
	v_mfma_f32_16x16x32_bf16 v[2:5], v[226:229], v[190:193], v[2:5]
	v_mfma_f32_16x16x32_bf16 v[46:49], v[222:225], v[170:173], v[46:49]
	v_mfma_f32_16x16x32_bf16 v[42:45], v[244:247], v[170:173], v[42:45]
	v_mfma_f32_16x16x32_bf16 v[30:33], v[222:225], v[178:181], v[30:33]
	v_mfma_f32_16x16x32_bf16 v[26:29], v[244:247], v[178:181], v[26:29]
	v_mfma_f32_16x16x32_bf16 v[14:17], v[222:225], v[186:189], v[14:17]
	v_mfma_f32_16x16x32_bf16 v[10:13], v[244:247], v[186:189], v[10:13]
	v_mfma_f32_16x16x32_bf16 v[6:9], v[222:225], v[214:217], v[6:9]
	v_mfma_f32_16x16x32_bf16 v[2:5], v[244:247], v[214:217], v[2:5]
	s_setprio 0
	s_add_i32 s45, 0, 0x18000
	v_add_u32_e32 v149, s45, v146
	s_barrier
	ds_read_b128 v[150:153], v149
	ds_read_b128 v[154:157], v149 offset:1024
	ds_read_b128 v[158:161], v149 offset:2048
	ds_read_b128 v[162:165], v149 offset:3072
	s_mov_b32 m0, s51
	v_lshl_add_u64 v[218:219], v[200:201], 0, s[24:25]
	ds_read_b128 v[166:169], v148 offset:32768
	ds_read_b128 v[170:173], v148 offset:33792
	ds_read_b128 v[174:177], v148 offset:34816
	ds_read_b128 v[178:181], v148 offset:35840
	ds_read_b128 v[182:185], v148 offset:36864
	ds_read_b128 v[186:189], v148 offset:37888
	ds_read_b128 v[190:193], v148 offset:38912
	ds_read_b128 v[214:217], v148 offset:39936
	global_load_lds_dwordx4 v[218:219], off
	v_lshl_add_u64 v[218:219], v[200:201], 0, s[28:29]
	s_mov_b32 m0, s52
	s_nop 0
	global_load_lds_dwordx4 v[218:219], off
	s_waitcnt lgkmcnt(8)
	s_barrier
	s_waitcnt lgkmcnt(0)
	s_setprio 1
	s_waitcnt lgkmcnt(0)
	v_mfma_f32_16x16x32_bf16 v[126:129], v[150:153], v[166:169], v[126:129]
	v_mfma_f32_16x16x32_bf16 v[122:125], v[158:161], v[166:169], v[122:125]
	v_mfma_f32_16x16x32_bf16 v[118:121], v[150:153], v[174:177], v[118:121]
	v_mfma_f32_16x16x32_bf16 v[114:117], v[158:161], v[174:177], v[114:117]
	v_mfma_f32_16x16x32_bf16 v[102:105], v[150:153], v[182:185], v[102:105]
	v_mfma_f32_16x16x32_bf16 v[98:101], v[158:161], v[182:185], v[98:101]
	v_mfma_f32_16x16x32_bf16 v[86:89], v[150:153], v[190:193], v[86:89]
	v_mfma_f32_16x16x32_bf16 v[82:85], v[158:161], v[190:193], v[82:85]
	v_mfma_f32_16x16x32_bf16 v[126:129], v[154:157], v[170:173], v[126:129]
	v_mfma_f32_16x16x32_bf16 v[122:125], v[162:165], v[170:173], v[122:125]
	v_mfma_f32_16x16x32_bf16 v[118:121], v[154:157], v[178:181], v[118:121]
	v_mfma_f32_16x16x32_bf16 v[114:117], v[162:165], v[178:181], v[114:117]
	v_mfma_f32_16x16x32_bf16 v[102:105], v[154:157], v[186:189], v[102:105]
	v_mfma_f32_16x16x32_bf16 v[98:101], v[162:165], v[186:189], v[98:101]
	v_mfma_f32_16x16x32_bf16 v[86:89], v[154:157], v[214:217], v[86:89]
	v_mfma_f32_16x16x32_bf16 v[82:85], v[162:165], v[214:217], v[82:85]
	s_setprio 0
	s_barrier
	s_add_i32 s60, 0, 0x1c000
	s_add_i32 s45, s45, s48
	v_add_u32_e32 v149, s60, v146
	v_lshl_add_u64 v[230:231], v[198:199], 0, s[26:27]
	s_mov_b32 m0, s45
	ds_read_b128 v[218:221], v149
	ds_read_b128 v[222:225], v149 offset:1024
	ds_read_b128 v[226:229], v149 offset:2048
	ds_read_b128 v[244:247], v149 offset:3072
	global_load_lds_dwordx4 v[230:231], off
	v_lshl_add_u64 v[230:231], v[198:199], 0, s[72:73]
	s_add_i32 m0, s45, 0x2000
	s_nop 0
	global_load_lds_dwordx4 v[230:231], off
	s_barrier
	s_waitcnt lgkmcnt(0)
	s_setprio 1
	s_waitcnt lgkmcnt(0)
	v_mfma_f32_16x16x32_bf16 v[110:113], v[218:221], v[166:169], v[110:113]
	v_mfma_f32_16x16x32_bf16 v[106:109], v[226:229], v[166:169], v[106:109]
	v_mfma_f32_16x16x32_bf16 v[94:97], v[218:221], v[174:177], v[94:97]
	v_mfma_f32_16x16x32_bf16 v[90:93], v[226:229], v[174:177], v[90:93]
	v_mfma_f32_16x16x32_bf16 v[78:81], v[218:221], v[182:185], v[78:81]
	v_mfma_f32_16x16x32_bf16 v[74:77], v[226:229], v[182:185], v[74:77]
	v_mfma_f32_16x16x32_bf16 v[70:73], v[218:221], v[190:193], v[70:73]
	v_mfma_f32_16x16x32_bf16 v[66:69], v[226:229], v[190:193], v[66:69]
	v_mfma_f32_16x16x32_bf16 v[110:113], v[222:225], v[170:173], v[110:113]
	v_mfma_f32_16x16x32_bf16 v[106:109], v[244:247], v[170:173], v[106:109]
	v_mfma_f32_16x16x32_bf16 v[94:97], v[222:225], v[178:181], v[94:97]
	v_mfma_f32_16x16x32_bf16 v[90:93], v[244:247], v[178:181], v[90:93]
	v_mfma_f32_16x16x32_bf16 v[78:81], v[222:225], v[186:189], v[78:81]
	v_mfma_f32_16x16x32_bf16 v[74:77], v[244:247], v[186:189], v[74:77]
	v_mfma_f32_16x16x32_bf16 v[70:73], v[222:225], v[214:217], v[70:73]
	v_mfma_f32_16x16x32_bf16 v[66:69], v[244:247], v[214:217], v[66:69]
	s_setprio 0
	s_mov_b32 m0, s53
	v_lshl_add_u64 v[230:231], v[200:201], 0, s[26:27]
	s_barrier
	ds_read_b128 v[166:169], v148 offset:49152
	ds_read_b128 v[170:173], v148 offset:50176
	ds_read_b128 v[174:177], v148 offset:51200
	ds_read_b128 v[178:181], v148 offset:52224
	ds_read_b128 v[182:185], v148 offset:53248
	ds_read_b128 v[186:189], v148 offset:54272
	ds_read_b128 v[190:193], v148 offset:55296
	ds_read_b128 v[214:217], v148 offset:56320
	global_load_lds_dwordx4 v[230:231], off
	v_lshl_add_u64 v[200:201], v[200:201], 0, s[36:37]
	s_mov_b32 m0, s54
	s_nop 0
	global_load_lds_dwordx4 v[200:201], off
	s_barrier
; #define PG8_STAGE(bufoff, gbase, voff) do { _Pragma("unroll") for (int _i = 0; _i < 2; ++_i) \
;         __builtin_amdgcn_global_load_lds((const unsigned*)((const char*)(gbase) + (size_t)_i * p64##voff + (v##voff##_)), (LAS unsigned*)(lds + (bufoff) + ldsw + _i * 8192), 16, 0, 0); } while (0)
; #define PG8_MMA(ai, bj, At, Bt) do { __builtin_amdgcn_s_setprio(1); _Pragma("unroll") for (int m = 0; m < 4; ++m) _Pragma("unroll") for (int n = 0; n < 2; ++n) _Pragma("unroll") for (int k = 0; k < 2; ++k) \
;         acc[ai][bj][m][n] = __builtin_amdgcn_mfma_f32_16x16x32_bf16(Bt[n][k], At[m][k], acc[ai][bj][m][n], 0, 0, 0); __builtin_amdgcn_s_setprio(0); } while (0)
; #define PG8_WAIT_V(n) asm volatile("s_waitcnt vmcnt(" #n ")" ::: "memory")
; #define PG8_WAIT_L(n) asm volatile("s_waitcnt lgkmcnt(" #n ")" ::: "memory")
; #define PG8_BAR __builtin_amdgcn_s_barrier()
; #define PG8_SCHED __builtin_amdgcn_sched_barrier(0)
; template <class Epi, class Sched>
; DI void gemm_phase(LAS unsigned char* lds, const Gemm g, const Sched& S, const Epi& E, const int tid) {
;     ...
;             PG8_BAR; PG8_WAIT_L(0); PG8_MMA(1, 0, At, B0); PG8_BAR; PG8_SCHED;
;             PG8_STAGE(PG8_SB(1, 1), b3 + hstepB, offB);
;             PG8_WAIT_V(6); PG8_BAR; PG8_MMA(1, 1, At, B1); PG8_BAR;
	s_waitcnt lgkmcnt(0)
	s_setprio 1
	s_waitcnt lgkmcnt(0)
	v_mfma_f32_16x16x32_bf16 v[62:65], v[150:153], v[166:169], v[62:65]
	v_mfma_f32_16x16x32_bf16 v[58:61], v[158:161], v[166:169], v[58:61]
	v_mfma_f32_16x16x32_bf16 v[54:57], v[150:153], v[174:177], v[54:57]
	v_mfma_f32_16x16x32_bf16 v[50:53], v[158:161], v[174:177], v[50:53]
	v_mfma_f32_16x16x32_bf16 v[38:41], v[150:153], v[182:185], v[38:41]
	v_mfma_f32_16x16x32_bf16 v[34:37], v[158:161], v[182:185], v[34:37]
	v_mfma_f32_16x16x32_bf16 v[22:25], v[150:153], v[190:193], v[22:25]
	v_mfma_f32_16x16x32_bf16 v[18:21], v[158:161], v[190:193], v[18:21]
	v_mfma_f32_16x16x32_bf16 v[62:65], v[154:157], v[170:173], v[62:65]
	v_mfma_f32_16x16x32_bf16 v[58:61], v[162:165], v[170:173], v[58:61]
	v_mfma_f32_16x16x32_bf16 v[54:57], v[154:157], v[178:181], v[54:57]
	v_mfma_f32_16x16x32_bf16 v[50:53], v[162:165], v[178:181], v[50:53]
	v_mfma_f32_16x16x32_bf16 v[38:41], v[154:157], v[186:189], v[38:41]
	v_mfma_f32_16x16x32_bf16 v[34:37], v[162:165], v[186:189], v[34:37]
	v_mfma_f32_16x16x32_bf16 v[22:25], v[154:157], v[214:217], v[22:25]
	v_mfma_f32_16x16x32_bf16 v[18:21], v[162:165], v[214:217], v[18:21]
	s_setprio 0
	s_barrier
	s_add_i32 s45, s60, s48
	v_lshl_add_u64 v[150:151], v[198:199], 0, s[66:67]
	s_mov_b32 m0, s45
	s_nop 0
	global_load_lds_dwordx4 v[150:151], off
	v_lshl_add_u64 v[150:151], v[198:199], 0, s[74:75]
	s_add_i32 m0, s45, 0x2000
	s_nop 0
	global_load_lds_dwordx4 v[150:151], off
	s_waitcnt vmcnt(6)
	s_barrier
	s_setprio 1
	v_mfma_f32_16x16x32_bf16 v[46:49], v[218:221], v[166:169], v[46:49]
	v_mfma_f32_16x16x32_bf16 v[42:45], v[226:229], v[166:169], v[42:45]
	v_mfma_f32_16x16x32_bf16 v[30:33], v[218:221], v[174:177], v[30:33]
	v_mfma_f32_16x16x32_bf16 v[26:29], v[226:229], v[174:177], v[26:29]
	v_mfma_f32_16x16x32_bf16 v[14:17], v[218:221], v[182:185], v[14:17]
	v_mfma_f32_16x16x32_bf16 v[10:13], v[226:229], v[182:185], v[10:13]
	v_mfma_f32_16x16x32_bf16 v[6:9], v[218:221], v[190:193], v[6:9]
	v_mfma_f32_16x16x32_bf16 v[2:5], v[226:229], v[190:193], v[2:5]
	v_mfma_f32_16x16x32_bf16 v[46:49], v[222:225], v[170:173], v[46:49]
	v_mfma_f32_16x16x32_bf16 v[42:45], v[244:247], v[170:173], v[42:45]
	v_mfma_f32_16x16x32_bf16 v[30:33], v[222:225], v[178:181], v[30:33]
	v_mfma_f32_16x16x32_bf16 v[26:29], v[244:247], v[178:181], v[26:29]
	v_mfma_f32_16x16x32_bf16 v[14:17], v[222:225], v[186:189], v[14:17]
	v_mfma_f32_16x16x32_bf16 v[10:13], v[244:247], v[186:189], v[10:13]
	v_mfma_f32_16x16x32_bf16 v[6:9], v[222:225], v[214:217], v[6:9]
	v_mfma_f32_16x16x32_bf16 v[2:5], v[244:247], v[214:217], v[2:5]
	s_setprio 0
	s_add_i32 s44, s44, 2
	s_add_u32 s0, s0, 0x100
	s_addc_u32 s1, s1, 0
	s_add_u32 s42, s42, 0x100
	s_addc_u32 s43, s43, 0
	s_cmp_gt_u32 s44, 3
	s_barrier
	s_cbranch_scc0 .LBB0_146
; DI unsigned pk2(float lo, float hi) { f32x2 v = {lo, hi}; bf2_t b = __builtin_convertvector(v, bf2_t); return __builtin_bit_cast(unsigned, b); }
;     DI void operator()(const f32x4 (&acc)[2][2][4][2], const Unit& u, int wr, int wc, int fr, int fq) const {
;         const int row0 = u.pm * BM + wr * 64 + fr, col0 = u.pn * BM + wc * 32 + 8 * fq;
; #pragma unroll
;         for (int ai = 0; ai < 2; ++ai)
; #pragma unroll
;             for (int m = 0; m < 4; ++m) { bf16_t* rowp = O + (size_t)(row0 + ai * HALF + m * 16) * ldc + col0;
; #pragma unroll
;                 for (int bj = 0; bj < 2; ++bj) { f32x4 v0 = acc[ai][bj][m][0], v1 = acc[ai][bj][m][1];
;                     if (ACT == 1) {
; #pragma unroll
;                         for (int j = 0; j < 4; ++j) { float a = fmaxf(v0[j], 0.f), b = fmaxf(v1[j], 0.f); v0[j] = a * a; v1[j] = b * b; } }
;                     u32x4 w; w.x = pk2(v0[0], v0[1]); w.y = pk2(v0[2], v0[3]); w.z = pk2(v1[0], v1[1]); w.w = pk2(v1[2], v1[3]);
;                     *(u32x4*)(rowp + bj * HALF) = w; } }
	v_readlane_b32 s0, v254, 55
	v_lshl_add_u32 v149, s58, 8, v133
	v_lshl_or_b32 v150, s57, 8, v147
	v_readlane_b32 s1, v254, 56
	v_ashrrev_i32_e32 v151, 31, v150
	v_cvt_pk_bf16_f32 v70, v70, v71
	v_mov_b64_e32 v[152:153], s[0:1]
	v_cvt_pk_bf16_f32 v71, v72, v73
	v_cvt_pk_bf16_f32 v72, v66, v67
	v_add_u32_e32 v66, 0x80, v149
	v_mad_i64_i32 v[154:155], s[0:1], v149, s84, v[152:153]
	v_lshlrev_b64 v[150:151], 1, v[150:151]
	v_cvt_pk_bf16_f32 v110, v110, v111
	v_cvt_pk_bf16_f32 v111, v112, v113
	v_cvt_pk_bf16_f32 v112, v106, v107
	v_or_b32_e32 v106, 16, v149
	v_mad_i64_i32 v[66:67], s[0:1], v66, s84, v[152:153]
	v_cvt_pk_bf16_f32 v46, v46, v47
	v_cvt_pk_bf16_f32 v47, v48, v49
	v_cvt_pk_bf16_f32 v48, v42, v43
	v_add_u32_e32 v42, 0x90, v149
	v_lshl_add_u64 v[154:155], v[154:155], 0, v[150:151]
	v_cvt_pk_bf16_f32 v113, v108, v109
	v_mad_i64_i32 v[106:107], s[0:1], v106, s84, v[152:153]
	v_cvt_pk_bf16_f32 v94, v94, v95
	v_cvt_pk_bf16_f32 v95, v96, v97
	v_cvt_pk_bf16_f32 v96, v90, v91
	v_or_b32_e32 v90, 32, v149
	v_lshl_add_u64 v[66:67], v[66:67], 0, v[150:151]
	v_cvt_pk_bf16_f32 v49, v44, v45
	v_mad_i64_i32 v[42:43], s[0:1], v42, s84, v[152:153]
	v_cvt_pk_bf16_f32 v30, v30, v31
	v_cvt_pk_bf16_f32 v31, v32, v33
	v_cvt_pk_bf16_f32 v32, v26, v27
	v_add_u32_e32 v26, 0xa0, v149
	global_store_dwordx4 v[154:155], v[110:113], off offset:256 nt
	v_cvt_pk_bf16_f32 v97, v92, v93
	v_mad_i64_i32 v[90:91], s[0:1], v90, s84, v[152:153]
	v_lshl_add_u64 v[110:111], v[106:107], 0, v[150:151]
	v_cvt_pk_bf16_f32 v78, v78, v79
	v_cvt_pk_bf16_f32 v79, v80, v81
	v_cvt_pk_bf16_f32 v80, v74, v75
	v_or_b32_e32 v74, 48, v149
	global_store_dwordx4 v[66:67], v[46:49], off offset:256 nt
	v_cvt_pk_bf16_f32 v33, v28, v29
	v_mad_i64_i32 v[26:27], s[0:1], v26, s84, v[152:153]
	v_lshl_add_u64 v[46:47], v[42:43], 0, v[150:151]
	v_cvt_pk_bf16_f32 v14, v14, v15
	v_cvt_pk_bf16_f32 v15, v16, v17
	v_cvt_pk_bf16_f32 v16, v10, v11
	v_add_u32_e32 v10, 0xb0, v149
	global_store_dwordx4 v[110:111], v[94:97], off offset:256 nt
	v_cvt_pk_bf16_f32 v81, v76, v77
	v_mad_i64_i32 v[74:75], s[0:1], v74, s84, v[152:153]
	v_lshl_add_u64 v[94:95], v[90:91], 0, v[150:151]
	global_store_dwordx4 v[46:47], v[30:33], off offset:256 nt
	v_cvt_pk_bf16_f32 v17, v12, v13
	v_mad_i64_i32 v[10:11], s[0:1], v10, s84, v[152:153]
	v_lshl_add_u64 v[30:31], v[26:27], 0, v[150:151]
	v_readlane_b32 s60, v254, 63
	v_cvt_pk_bf16_f32 v126, v126, v127
	v_cvt_pk_bf16_f32 v127, v128, v129
	v_cvt_pk_bf16_f32 v128, v122, v123
	v_cvt_pk_bf16_f32 v129, v124, v125
	v_cvt_pk_bf16_f32 v106, v118, v119
	v_cvt_pk_bf16_f32 v107, v120, v121
	v_cvt_pk_bf16_f32 v108, v114, v115
	v_cvt_pk_bf16_f32 v109, v116, v117
	v_cvt_pk_bf16_f32 v90, v102, v103
	v_cvt_pk_bf16_f32 v91, v104, v105
	v_cvt_pk_bf16_f32 v92, v98, v99
	v_cvt_pk_bf16_f32 v93, v100, v101
	global_store_dwordx4 v[94:95], v[78:81], off offset:256 nt
	v_cvt_pk_bf16_f32 v76, v82, v83
	v_cvt_pk_bf16_f32 v77, v84, v85
	v_lshl_add_u64 v[78:79], v[74:75], 0, v[150:151]
	v_cvt_pk_bf16_f32 v74, v86, v87
	v_cvt_pk_bf16_f32 v75, v88, v89
	v_cvt_pk_bf16_f32 v73, v68, v69
	v_cvt_pk_bf16_f32 v62, v62, v63
	v_cvt_pk_bf16_f32 v63, v64, v65
	v_cvt_pk_bf16_f32 v64, v58, v59
	v_cvt_pk_bf16_f32 v65, v60, v61
	v_cvt_pk_bf16_f32 v42, v54, v55
	v_cvt_pk_bf16_f32 v43, v56, v57
	v_cvt_pk_bf16_f32 v44, v50, v51
	v_cvt_pk_bf16_f32 v45, v52, v53
	v_cvt_pk_bf16_f32 v26, v38, v39
	v_cvt_pk_bf16_f32 v27, v40, v41
	v_cvt_pk_bf16_f32 v28, v34, v35
	v_cvt_pk_bf16_f32 v29, v36, v37
	global_store_dwordx4 v[30:31], v[14:17], off offset:256 nt
	v_cvt_pk_bf16_f32 v12, v18, v19
	v_cvt_pk_bf16_f32 v13, v20, v21
	v_lshl_add_u64 v[14:15], v[10:11], 0, v[150:151]
	v_cvt_pk_bf16_f32 v10, v22, v23
	v_cvt_pk_bf16_f32 v11, v24, v25
	v_cvt_pk_bf16_f32 v6, v6, v7
	v_cvt_pk_bf16_f32 v7, v8, v9
	v_cvt_pk_bf16_f32 v8, v2, v3
	v_cvt_pk_bf16_f32 v9, v4, v5
	s_and_b64 vcc, exec, s[40:41]
	s_mov_b32 s57, s56
	s_mov_b32 s58, s4
	s_mov_b64 s[42:43], s[6:7]
	s_mov_b64 s[44:45], s[8:9]
	v_readlane_b32 s61, v255, 0
	v_readlane_b32 s62, v255, 1
	v_readlane_b32 s63, v255, 2
	v_readlane_b32 s64, v255, 3
	v_readlane_b32 s65, v255, 4
	v_readlane_b32 s66, v255, 5
	v_readlane_b32 s67, v255, 6
	v_readlane_b32 s68, v255, 7
	v_readlane_b32 s69, v255, 8
	v_readlane_b32 s70, v255, 9
	v_readlane_b32 s71, v255, 10
	v_readlane_b32 s72, v255, 11
	v_readlane_b32 s73, v255, 12
	v_readlane_b32 s74, v255, 13
	v_readlane_b32 s75, v255, 14
	global_store_dwordx4 v[154:155], v[126:129], off nt
	global_store_dwordx4 v[110:111], v[106:109], off nt
	global_store_dwordx4 v[94:95], v[90:93], off nt
	global_store_dwordx4 v[78:79], v[74:77], off nt
	global_store_dwordx4 v[78:79], v[70:73], off offset:256 nt
	global_store_dwordx4 v[66:67], v[62:65], off nt
	global_store_dwordx4 v[46:47], v[42:45], off nt
	global_store_dwordx4 v[30:31], v[26:29], off nt
	global_store_dwordx4 v[14:15], v[10:13], off nt
	global_store_dwordx4 v[14:15], v[6:9], off offset:256 nt
	s_cbranch_vccz .LBB0_137
	s_waitcnt vmcnt(0)
	v_readlane_b32 s84, v254, 59
	s_cmpk_gt_u32 s2, 0xff
	v_readlane_b32 s85, v254, 60
	s_cbranch_scc1 .LBB0_150
	s_barrier

;     DI bool next(int i, Unit& u) const { const int L = i * G + c; if (L >= 256) return false; u.pm = 0; u.pn = L; u.bofs = ((long)((L >> 3) * 2048 + 2 * (L & 7)) * 1024) * 2; return true; }
;     DI bool next(int i, Unit& u) const { Unit v; if (!base.next(i / 3, v)) return false; u.pm = v.pm; u.pn = (i % 3) * 4 + v.pn; u.bofs = -1; return true; }
; #define PG8_STAGE(bufoff, gbase, voff) do { _Pragma("unroll") for (int _i = 0; _i < 2; ++_i) \
;         __builtin_amdgcn_global_load_lds((const unsigned*)((const char*)(gbase) + (size_t)_i * p64##voff + (v##voff##_)), (LAS unsigned*)(lds + (bufoff) + ldsw + _i * 8192), 16, 0, 0); } while (0)
; #define PG8_LDA(dst, b, h) do { _Pragma("unroll") for (int m = 0; m < 4; ++m) _Pragma("unroll") for (int k = 0; k < 2; ++k) dst[m][k] = *(const LAS bf16x8*)(lds + PG8_SA(b, h) + aoff + m * 2048 + k * 1024); } while (0)
; #define PG8_WAIT_V(n) asm volatile("s_waitcnt vmcnt(" #n ")" ::: "memory")
; #define PG8_WAIT_L(n) asm volatile("s_waitcnt lgkmcnt(" #n ")" ::: "memory")
; template <class Epi, class Sched>
; DI void gemm_phase(LAS unsigned char* lds, const Gemm g, const Sched& S, const Epi& E, const int tid) {
;     ...
;         const bool has_next = S.next(ui + 1, nxt);
;         const char* nA = has_next ? (const char*)g.A + (size_t)nxt.pm * tstepA : cA; const char* nB = has_next ? (const char*)g.Bt + (nxt.bofs >= 0 ? (size_t)nxt.bofs : (size_t)nxt.pn * tstepB) : cB;
;         for (int t = 0; t < nt; t += 2) {
;             const bool last = (t == nt - 2);
;             const char* a1 = cA + (size_t)(t + 1) * kstep;
;             const char* a2 = last ? nA : cA + (size_t)(t + 2) * kstep; const char* b2 = last ? nB : cB + (size_t)(t + 2) * kstep;
;             const char* a3 = a2 + kstep; const char* b3 = b2 + kstep;
;             PG8_LDB(B0, 0, 0); PG8_SCHED; PG8_LDA(At, 0, 0); PG8_STAGE(PG8_SA(1, 1), a1 + hstepA, offA);
;             PG8_WAIT_L(8); PG8_BAR; PG8_WAIT_L(0); PG8_MMA(0, 0, At, B0); PG8_BAR; PG8_SCHED;
;             PG8_LDB(B1, 0, 1); PG8_STAGE(PG8_SB(0, 0), b2, offB);
;             PG8_BAR; PG8_WAIT_L(0); PG8_MMA(0, 1, At, B1); PG8_BAR;
;             PG8_LDA(At, 0, 1); PG8_STAGE(PG8_SA(0, 0), a2, offA);
;             PG8_BAR; PG8_WAIT_L(0); PG8_MMA(1, 0, At, B0); PG8_BAR; PG8_SCHED;
;             PG8_STAGE(PG8_SB(0, 1), b2 + hstepB, offB);
;             PG8_WAIT_V(6); PG8_BAR; PG8_MMA(1, 1, At, B1); PG8_BAR;
.LBB0_162:
	s_add_u32 s50, s44, s2
	s_addc_u32 s51, s45, 0
	s_add_u32 s67, s50, 0x100
	s_addc_u32 s68, s51, 0
	s_and_b64 s[50:51], s[48:49], exec
	s_cselect_b32 s50, s65, s67
	s_cselect_b32 s51, s7, s68
	s_add_u32 s67, s0, s2
	s_addc_u32 s68, s1, 0
	s_add_u32 s67, s67, 0x100
	s_addc_u32 s68, s68, 0
	s_add_i32 s72, 0, 0x10000
	v_add_u32_e32 v162, s72, v147
	ds_read_b128 v[150:153], v162
	ds_read_b128 v[154:157], v162 offset:1024
	ds_read_b128 v[158:161], v162 offset:2048
	ds_read_b128 v[162:165], v162 offset:3072
	s_and_b64 s[48:49], s[48:49], exec
	s_cselect_b32 s48, s66, s67
	s_cselect_b32 s49, s5, s68
	s_add_i32 s76, 0, 0x14000
	s_add_i32 s69, 0, 0x18000
	s_add_i32 s67, 0, 0x1c000
	s_add_i32 s77, s72, s55
	s_add_i32 s71, s76, s55
	s_add_i32 s68, s69, s55
	s_add_i32 s73, s67, s55
	s_add_i32 m0, s56, 0xc000
	s_add_i32 s75, s56, 0xe000
	s_add_i32 s74, s77, 0x2000
	s_add_i32 s70, s71, 0x2000
	s_add_i32 s78, s68, 0x2000
	s_add_i32 s72, s73, 0x2000
	v_lshl_add_u64 v[198:199], v[132:133], 0, s[2:3]
	v_lshl_add_u64 v[200:201], v[198:199], 0, s[34:35]
	ds_read_b128 v[166:169], v149
	ds_read_b128 v[170:173], v149 offset:1024
	ds_read_b128 v[174:177], v149 offset:2048
	ds_read_b128 v[178:181], v149 offset:3072
	ds_read_b128 v[182:185], v149 offset:4096
	ds_read_b128 v[186:189], v149 offset:5120
	ds_read_b128 v[190:193], v149 offset:6144
	ds_read_b128 v[214:217], v149 offset:7168
	global_load_lds_dwordx4 v[200:201], off
	v_lshl_add_u64 v[198:199], v[198:199], 0, s[18:19]
	s_mov_b32 m0, s75
	s_nop 0
	global_load_lds_dwordx4 v[198:199], off
	s_waitcnt lgkmcnt(8)
	s_barrier
	s_waitcnt lgkmcnt(0)
	s_setprio 1
	s_waitcnt lgkmcnt(0)
	v_mfma_f32_16x16x32_bf16 v[126:129], v[150:153], v[166:169], v[126:129]
	v_mfma_f32_16x16x32_bf16 v[122:125], v[158:161], v[166:169], v[122:125]
	v_mfma_f32_16x16x32_bf16 v[118:121], v[150:153], v[174:177], v[118:121]
	v_mfma_f32_16x16x32_bf16 v[114:117], v[158:161], v[174:177], v[114:117]
	v_mfma_f32_16x16x32_bf16 v[102:105], v[150:153], v[182:185], v[102:105]
	v_mfma_f32_16x16x32_bf16 v[98:101], v[158:161], v[182:185], v[98:101]
	v_mfma_f32_16x16x32_bf16 v[86:89], v[150:153], v[190:193], v[86:89]
	v_mfma_f32_16x16x32_bf16 v[82:85], v[158:161], v[190:193], v[82:85]
	v_mfma_f32_16x16x32_bf16 v[126:129], v[154:157], v[170:173], v[126:129]
	v_mfma_f32_16x16x32_bf16 v[122:125], v[162:165], v[170:173], v[122:125]
	v_mfma_f32_16x16x32_bf16 v[118:121], v[154:157], v[178:181], v[118:121]
	v_mfma_f32_16x16x32_bf16 v[114:117], v[162:165], v[178:181], v[114:117]
	v_mfma_f32_16x16x32_bf16 v[102:105], v[154:157], v[186:189], v[102:105]
	v_mfma_f32_16x16x32_bf16 v[98:101], v[162:165], v[186:189], v[98:101]
	v_mfma_f32_16x16x32_bf16 v[86:89], v[154:157], v[214:217], v[86:89]
	v_mfma_f32_16x16x32_bf16 v[82:85], v[162:165], v[214:217], v[82:85]
	s_setprio 0
	s_barrier
	v_add_u32_e32 v198, s76, v147
	s_mov_b32 m0, s77
	ds_read_b128 v[218:221], v198
	ds_read_b128 v[222:225], v198 offset:1024
	ds_read_b128 v[226:229], v198 offset:2048
	ds_read_b128 v[244:247], v198 offset:3072
	v_lshl_add_u64 v[198:199], s[48:49], 0, v[130:131]
	global_load_lds_dwordx4 v[198:199], off
	v_lshl_add_u64 v[200:201], v[198:199], 0, s[38:39]
	s_mov_b32 m0, s74
	s_nop 0
	global_load_lds_dwordx4 v[200:201], off
	s_barrier
	s_waitcnt lgkmcnt(0)
	s_setprio 1
	s_waitcnt lgkmcnt(0)
	v_mfma_f32_16x16x32_bf16 v[110:113], v[218:221], v[166:169], v[110:113]
	v_mfma_f32_16x16x32_bf16 v[106:109], v[226:229], v[166:169], v[106:109]
	v_mfma_f32_16x16x32_bf16 v[94:97], v[218:221], v[174:177], v[94:97]
	v_mfma_f32_16x16x32_bf16 v[90:93], v[226:229], v[174:177], v[90:93]
	v_mfma_f32_16x16x32_bf16 v[78:81], v[218:221], v[182:185], v[78:81]
	v_mfma_f32_16x16x32_bf16 v[74:77], v[226:229], v[182:185], v[74:77]
	v_mfma_f32_16x16x32_bf16 v[70:73], v[218:221], v[190:193], v[70:73]
	v_mfma_f32_16x16x32_bf16 v[66:69], v[226:229], v[190:193], v[66:69]
	v_mfma_f32_16x16x32_bf16 v[110:113], v[222:225], v[170:173], v[110:113]
	v_mfma_f32_16x16x32_bf16 v[106:109], v[244:247], v[170:173], v[106:109]
	v_mfma_f32_16x16x32_bf16 v[94:97], v[222:225], v[178:181], v[94:97]
	v_mfma_f32_16x16x32_bf16 v[90:93], v[244:247], v[178:181], v[90:93]
	v_mfma_f32_16x16x32_bf16 v[78:81], v[222:225], v[186:189], v[78:81]
	v_mfma_f32_16x16x32_bf16 v[74:77], v[244:247], v[186:189], v[74:77]
	v_mfma_f32_16x16x32_bf16 v[70:73], v[222:225], v[214:217], v[70:73]
	v_mfma_f32_16x16x32_bf16 v[66:69], v[244:247], v[214:217], v[66:69]
	s_setprio 0
	s_mov_b32 m0, s56
	v_lshl_add_u64 v[200:201], s[50:51], 0, v[212:213]
	s_barrier
	ds_read_b128 v[166:169], v149 offset:16384
	ds_read_b128 v[170:173], v149 offset:17408
	ds_read_b128 v[174:177], v149 offset:18432
	ds_read_b128 v[178:181], v149 offset:19456
	ds_read_b128 v[182:185], v149 offset:20480
	ds_read_b128 v[186:189], v149 offset:21504
	ds_read_b128 v[190:193], v149 offset:22528
	ds_read_b128 v[214:217], v149 offset:23552
	global_load_lds_dwordx4 v[200:201], off
	v_lshl_add_u64 v[230:231], v[200:201], 0, s[10:11]
	s_mov_b32 m0, s57
	s_nop 0
	global_load_lds_dwordx4 v[230:231], off
	s_barrier
; #define PG8_STAGE(bufoff, gbase, voff) do { _Pragma("unroll") for (int _i = 0; _i < 2; ++_i) \
;         __builtin_amdgcn_global_load_lds((const unsigned*)((const char*)(gbase) + (size_t)_i * p64##voff + (v##voff##_)), (LAS unsigned*)(lds + (bufoff) + ldsw + _i * 8192), 16, 0, 0); } while (0)
; #define PG8_LDA(dst, b, h) do { _Pragma("unroll") for (int m = 0; m < 4; ++m) _Pragma("unroll") for (int k = 0; k < 2; ++k) dst[m][k] = *(const LAS bf16x8*)(lds + PG8_SA(b, h) + aoff + m * 2048 + k * 1024); } while (0)
; #define PG8_LDB(dst, b, h) do { _Pragma("unroll") for (int n = 0; n < 2; ++n) _Pragma("unroll") for (int k = 0; k < 2; ++k) dst[n][k] = *(const LAS bf16x8*)(lds + PG8_SB(b, h) + boff + n * 2048 + k * 1024); } while (0)
; #define PG8_MMA(ai, bj, At, Bt) do { __builtin_amdgcn_s_setprio(1); _Pragma("unroll") for (int m = 0; m < 4; ++m) _Pragma("unroll") for (int n = 0; n < 2; ++n) _Pragma("unroll") for (int k = 0; k < 2; ++k) \
;         acc[ai][bj][m][n] = __builtin_amdgcn_mfma_f32_16x16x32_bf16(Bt[n][k], At[m][k], acc[ai][bj][m][n], 0, 0, 0); __builtin_amdgcn_s_setprio(0); } while (0)
; #define PG8_WAIT_V(n) asm volatile("s_waitcnt vmcnt(" #n ")" ::: "memory")
; #define PG8_WAIT_L(n) asm volatile("s_waitcnt lgkmcnt(" #n ")" ::: "memory")
; #define PG8_BAR __builtin_amdgcn_s_barrier()
; #define PG8_SCHED __builtin_amdgcn_sched_barrier(0)
; template <class Epi, class Sched>
; DI void gemm_phase(LAS unsigned char* lds, const Gemm g, const Sched& S, const Epi& E, const int tid) {
;     ...
;             PG8_STAGE(PG8_SB(0, 1), b2 + hstepB, offB);
;             PG8_WAIT_V(6); PG8_BAR; PG8_MMA(1, 1, At, B1); PG8_BAR;
;             PG8_LDB(B0, 1, 0); PG8_SCHED; PG8_LDA(At, 1, 0); PG8_STAGE(PG8_SA(0, 1), a2 + hstepA, offA);
;             PG8_WAIT_L(8); PG8_BAR; PG8_WAIT_L(0); PG8_MMA(0, 0, At, B0); PG8_BAR; PG8_SCHED;
;             PG8_LDB(B1, 1, 1); PG8_STAGE(PG8_SB(1, 0), b3, offB);
;             PG8_BAR; PG8_WAIT_L(0); PG8_MMA(0, 1, At, B1); PG8_BAR;
;             PG8_LDA(At, 1, 1); PG8_STAGE(PG8_SA(1, 0), a3, offA);
;             PG8_BAR; PG8_WAIT_L(0); PG8_MMA(1, 0, At, B0); PG8_BAR; PG8_SCHED;
	s_waitcnt lgkmcnt(0)
	s_setprio 1
	s_waitcnt lgkmcnt(0)
	v_mfma_f32_16x16x32_bf16 v[62:65], v[150:153], v[166:169], v[62:65]
	v_mfma_f32_16x16x32_bf16 v[58:61], v[158:161], v[166:169], v[58:61]
	v_mfma_f32_16x16x32_bf16 v[54:57], v[150:153], v[174:177], v[54:57]
	v_mfma_f32_16x16x32_bf16 v[50:53], v[158:161], v[174:177], v[50:53]
	v_mfma_f32_16x16x32_bf16 v[38:41], v[150:153], v[182:185], v[38:41]
	v_mfma_f32_16x16x32_bf16 v[34:37], v[158:161], v[182:185], v[34:37]
	v_mfma_f32_16x16x32_bf16 v[22:25], v[150:153], v[190:193], v[22:25]
	v_mfma_f32_16x16x32_bf16 v[18:21], v[158:161], v[190:193], v[18:21]
	v_mfma_f32_16x16x32_bf16 v[62:65], v[154:157], v[170:173], v[62:65]
	v_mfma_f32_16x16x32_bf16 v[58:61], v[162:165], v[170:173], v[58:61]
	v_mfma_f32_16x16x32_bf16 v[54:57], v[154:157], v[178:181], v[54:57]
	v_mfma_f32_16x16x32_bf16 v[50:53], v[162:165], v[178:181], v[50:53]
	v_mfma_f32_16x16x32_bf16 v[38:41], v[154:157], v[186:189], v[38:41]
	v_mfma_f32_16x16x32_bf16 v[34:37], v[162:165], v[186:189], v[34:37]
	v_mfma_f32_16x16x32_bf16 v[22:25], v[154:157], v[214:217], v[22:25]
	v_mfma_f32_16x16x32_bf16 v[18:21], v[162:165], v[214:217], v[18:21]
	s_setprio 0
	s_barrier
	s_mov_b32 m0, s71
	v_lshl_add_u64 v[150:151], v[198:199], 0, s[52:53]
	global_load_lds_dwordx4 v[150:151], off
	v_lshl_add_u64 v[150:151], v[198:199], 0, s[82:83]
	s_mov_b32 m0, s70
	s_nop 0
	global_load_lds_dwordx4 v[150:151], off
	s_waitcnt vmcnt(6)
	s_barrier
	s_setprio 1
	v_mfma_f32_16x16x32_bf16 v[46:49], v[218:221], v[166:169], v[46:49]
	v_mfma_f32_16x16x32_bf16 v[42:45], v[226:229], v[166:169], v[42:45]
	v_mfma_f32_16x16x32_bf16 v[30:33], v[218:221], v[174:177], v[30:33]
	v_mfma_f32_16x16x32_bf16 v[26:29], v[226:229], v[174:177], v[26:29]
	v_mfma_f32_16x16x32_bf16 v[14:17], v[218:221], v[182:185], v[14:17]
	v_mfma_f32_16x16x32_bf16 v[10:13], v[226:229], v[182:185], v[10:13]
	v_mfma_f32_16x16x32_bf16 v[6:9], v[218:221], v[190:193], v[6:9]
	v_mfma_f32_16x16x32_bf16 v[2:5], v[226:229], v[190:193], v[2:5]
	v_mfma_f32_16x16x32_bf16 v[46:49], v[222:225], v[170:173], v[46:49]
	v_mfma_f32_16x16x32_bf16 v[42:45], v[244:247], v[170:173], v[42:45]
	v_mfma_f32_16x16x32_bf16 v[30:33], v[222:225], v[178:181], v[30:33]
	v_mfma_f32_16x16x32_bf16 v[26:29], v[244:247], v[178:181], v[26:29]
	v_mfma_f32_16x16x32_bf16 v[14:17], v[222:225], v[186:189], v[14:17]
	v_mfma_f32_16x16x32_bf16 v[10:13], v[244:247], v[186:189], v[10:13]
	v_mfma_f32_16x16x32_bf16 v[6:9], v[222:225], v[214:217], v[6:9]
	v_mfma_f32_16x16x32_bf16 v[2:5], v[244:247], v[214:217], v[2:5]
	s_setprio 0
	v_add_u32_e32 v162, s69, v147
	s_barrier
	ds_read_b128 v[150:153], v162
	ds_read_b128 v[154:157], v162 offset:1024
	ds_read_b128 v[158:161], v162 offset:2048
	ds_read_b128 v[162:165], v162 offset:3072
	s_mov_b32 m0, s58
	v_lshl_add_u64 v[218:219], v[200:201], 0, s[24:25]
	ds_read_b128 v[166:169], v149 offset:32768
	ds_read_b128 v[170:173], v149 offset:33792
	ds_read_b128 v[174:177], v149 offset:34816
	ds_read_b128 v[178:181], v149 offset:35840
	ds_read_b128 v[182:185], v149 offset:36864
	ds_read_b128 v[186:189], v149 offset:37888
	ds_read_b128 v[190:193], v149 offset:38912
	ds_read_b128 v[214:217], v149 offset:39936
	global_load_lds_dwordx4 v[218:219], off
	v_lshl_add_u64 v[218:219], v[200:201], 0, s[28:29]
	s_mov_b32 m0, s59
	s_nop 0
	global_load_lds_dwordx4 v[218:219], off
	s_waitcnt lgkmcnt(8)
	s_barrier
	s_waitcnt lgkmcnt(0)
	s_setprio 1
	s_waitcnt lgkmcnt(0)
	v_mfma_f32_16x16x32_bf16 v[126:129], v[150:153], v[166:169], v[126:129]
	v_mfma_f32_16x16x32_bf16 v[122:125], v[158:161], v[166:169], v[122:125]
	v_mfma_f32_16x16x32_bf16 v[118:121], v[150:153], v[174:177], v[118:121]
	v_mfma_f32_16x16x32_bf16 v[114:117], v[158:161], v[174:177], v[114:117]
	v_mfma_f32_16x16x32_bf16 v[102:105], v[150:153], v[182:185], v[102:105]
	v_mfma_f32_16x16x32_bf16 v[98:101], v[158:161], v[182:185], v[98:101]
	v_mfma_f32_16x16x32_bf16 v[86:89], v[150:153], v[190:193], v[86:89]
	v_mfma_f32_16x16x32_bf16 v[82:85], v[158:161], v[190:193], v[82:85]
	v_mfma_f32_16x16x32_bf16 v[126:129], v[154:157], v[170:173], v[126:129]
	v_mfma_f32_16x16x32_bf16 v[122:125], v[162:165], v[170:173], v[122:125]
	v_mfma_f32_16x16x32_bf16 v[118:121], v[154:157], v[178:181], v[118:121]
	v_mfma_f32_16x16x32_bf16 v[114:117], v[162:165], v[178:181], v[114:117]
	v_mfma_f32_16x16x32_bf16 v[102:105], v[154:157], v[186:189], v[102:105]
	v_mfma_f32_16x16x32_bf16 v[98:101], v[162:165], v[186:189], v[98:101]
	v_mfma_f32_16x16x32_bf16 v[86:89], v[154:157], v[214:217], v[86:89]
	v_mfma_f32_16x16x32_bf16 v[82:85], v[162:165], v[214:217], v[82:85]
	s_setprio 0
	s_barrier
	s_mov_b32 m0, s68
	s_mov_b64 s[48:49], 0x8080
	v_add_u32_e32 v211, s67, v147
	v_lshl_add_u64 v[230:231], v[198:199], 0, s[26:27]
	ds_read_b128 v[218:221], v211
	ds_read_b128 v[222:225], v211 offset:1024
	ds_read_b128 v[226:229], v211 offset:2048
	ds_read_b128 v[244:247], v211 offset:3072
	global_load_lds_dwordx4 v[230:231], off
	v_lshl_add_u64 v[230:231], v[198:199], 0, s[48:49]
	s_mov_b32 m0, s78
	s_mov_b64 s[50:51], 0x10080
	global_load_lds_dwordx4 v[230:231], off
	s_barrier
; #define PG8_STAGE(bufoff, gbase, voff) do { _Pragma("unroll") for (int _i = 0; _i < 2; ++_i) \
;         __builtin_amdgcn_global_load_lds((const unsigned*)((const char*)(gbase) + (size_t)_i * p64##voff + (v##voff##_)), (LAS unsigned*)(lds + (bufoff) + ldsw + _i * 8192), 16, 0, 0); } while (0)
; #define PG8_LDA(dst, b, h) do { _Pragma("unroll") for (int m = 0; m < 4; ++m) _Pragma("unroll") for (int k = 0; k < 2; ++k) dst[m][k] = *(const LAS bf16x8*)(lds + PG8_SA(b, h) + aoff + m * 2048 + k * 1024); } while (0)
; #define PG8_MMA(ai, bj, At, Bt) do { __builtin_amdgcn_s_setprio(1); _Pragma("unroll") for (int m = 0; m < 4; ++m) _Pragma("unroll") for (int n = 0; n < 2; ++n) _Pragma("unroll") for (int k = 0; k < 2; ++k) \
;         acc[ai][bj][m][n] = __builtin_amdgcn_mfma_f32_16x16x32_bf16(Bt[n][k], At[m][k], acc[ai][bj][m][n], 0, 0, 0); __builtin_amdgcn_s_setprio(0); } while (0)
; #define PG8_WAIT_V(n) asm volatile("s_waitcnt vmcnt(" #n ")" ::: "memory")
; #define PG8_WAIT_L(n) asm volatile("s_waitcnt lgkmcnt(" #n ")" ::: "memory")
; #define PG8_BAR __builtin_amdgcn_s_barrier()
; #define PG8_SCHED __builtin_amdgcn_sched_barrier(0)
; template <class Epi, class Sched>
; DI void gemm_phase(LAS unsigned char* lds, const Gemm g, const Sched& S, const Epi& E, const int tid) {
;     ...
;             PG8_LDA(At, 1, 1); PG8_STAGE(PG8_SA(1, 0), a3, offA);
;             PG8_BAR; PG8_WAIT_L(0); PG8_MMA(1, 0, At, B0); PG8_BAR; PG8_SCHED;
;             PG8_STAGE(PG8_SB(1, 1), b3 + hstepB, offB);
;             PG8_WAIT_V(6); PG8_BAR; PG8_MMA(1, 1, At, B1); PG8_BAR;
	s_waitcnt lgkmcnt(0)
	s_setprio 1
	s_waitcnt lgkmcnt(0)
	v_mfma_f32_16x16x32_bf16 v[110:113], v[218:221], v[166:169], v[110:113]
	v_mfma_f32_16x16x32_bf16 v[106:109], v[226:229], v[166:169], v[106:109]
	v_mfma_f32_16x16x32_bf16 v[94:97], v[218:221], v[174:177], v[94:97]
	v_mfma_f32_16x16x32_bf16 v[90:93], v[226:229], v[174:177], v[90:93]
	v_mfma_f32_16x16x32_bf16 v[78:81], v[218:221], v[182:185], v[78:81]
	v_mfma_f32_16x16x32_bf16 v[74:77], v[226:229], v[182:185], v[74:77]
	v_mfma_f32_16x16x32_bf16 v[70:73], v[218:221], v[190:193], v[70:73]
	v_mfma_f32_16x16x32_bf16 v[66:69], v[226:229], v[190:193], v[66:69]
	v_mfma_f32_16x16x32_bf16 v[110:113], v[222:225], v[170:173], v[110:113]
	v_mfma_f32_16x16x32_bf16 v[106:109], v[244:247], v[170:173], v[106:109]
	v_mfma_f32_16x16x32_bf16 v[94:97], v[222:225], v[178:181], v[94:97]
	v_mfma_f32_16x16x32_bf16 v[90:93], v[244:247], v[178:181], v[90:93]
	v_mfma_f32_16x16x32_bf16 v[78:81], v[222:225], v[186:189], v[78:81]
	v_mfma_f32_16x16x32_bf16 v[74:77], v[244:247], v[186:189], v[74:77]
	v_mfma_f32_16x16x32_bf16 v[70:73], v[222:225], v[214:217], v[70:73]
	v_mfma_f32_16x16x32_bf16 v[66:69], v[244:247], v[214:217], v[66:69]
	s_setprio 0
	s_mov_b32 m0, s60
	v_lshl_add_u64 v[230:231], v[200:201], 0, s[26:27]
	s_barrier
	ds_read_b128 v[166:169], v149 offset:49152
	ds_read_b128 v[170:173], v149 offset:50176
	ds_read_b128 v[174:177], v149 offset:51200
	ds_read_b128 v[178:181], v149 offset:52224
	ds_read_b128 v[182:185], v149 offset:53248
	ds_read_b128 v[186:189], v149 offset:54272
	ds_read_b128 v[190:193], v149 offset:55296
	ds_read_b128 v[214:217], v149 offset:56320
	global_load_lds_dwordx4 v[230:231], off
	v_lshl_add_u64 v[200:201], v[200:201], 0, s[36:37]
	s_mov_b32 m0, s61
	s_nop 0
	global_load_lds_dwordx4 v[200:201], off
	s_barrier
	s_waitcnt lgkmcnt(0)
	s_setprio 1
	s_waitcnt lgkmcnt(0)
	v_mfma_f32_16x16x32_bf16 v[62:65], v[150:153], v[166:169], v[62:65]
	v_mfma_f32_16x16x32_bf16 v[58:61], v[158:161], v[166:169], v[58:61]
	v_mfma_f32_16x16x32_bf16 v[54:57], v[150:153], v[174:177], v[54:57]
	v_mfma_f32_16x16x32_bf16 v[50:53], v[158:161], v[174:177], v[50:53]
	v_mfma_f32_16x16x32_bf16 v[38:41], v[150:153], v[182:185], v[38:41]
	v_mfma_f32_16x16x32_bf16 v[34:37], v[158:161], v[182:185], v[34:37]
	v_mfma_f32_16x16x32_bf16 v[22:25], v[150:153], v[190:193], v[22:25]
	v_mfma_f32_16x16x32_bf16 v[18:21], v[158:161], v[190:193], v[18:21]
	v_mfma_f32_16x16x32_bf16 v[62:65], v[154:157], v[170:173], v[62:65]
	v_mfma_f32_16x16x32_bf16 v[58:61], v[162:165], v[170:173], v[58:61]
	v_mfma_f32_16x16x32_bf16 v[54:57], v[154:157], v[178:181], v[54:57]
	v_mfma_f32_16x16x32_bf16 v[50:53], v[162:165], v[178:181], v[50:53]
	v_mfma_f32_16x16x32_bf16 v[38:41], v[154:157], v[186:189], v[38:41]
	v_mfma_f32_16x16x32_bf16 v[34:37], v[162:165], v[186:189], v[34:37]
	v_mfma_f32_16x16x32_bf16 v[22:25], v[154:157], v[214:217], v[22:25]
	v_mfma_f32_16x16x32_bf16 v[18:21], v[162:165], v[214:217], v[18:21]
	s_setprio 0
	s_barrier
	s_mov_b32 m0, s73
	v_lshl_add_u64 v[150:151], v[198:199], 0, s[50:51]
	global_load_lds_dwordx4 v[150:151], off
	v_lshl_add_u64 v[150:151], v[198:199], 0, s[96:97]
	s_mov_b32 m0, s72
	s_nop 0
	global_load_lds_dwordx4 v[150:151], off
	s_waitcnt vmcnt(6)
	s_barrier
	s_setprio 1
	v_mfma_f32_16x16x32_bf16 v[46:49], v[218:221], v[166:169], v[46:49]
	v_mfma_f32_16x16x32_bf16 v[42:45], v[226:229], v[166:169], v[42:45]
	v_mfma_f32_16x16x32_bf16 v[30:33], v[218:221], v[174:177], v[30:33]
	v_mfma_f32_16x16x32_bf16 v[26:29], v[226:229], v[174:177], v[26:29]
	v_mfma_f32_16x16x32_bf16 v[14:17], v[218:221], v[182:185], v[14:17]
	v_mfma_f32_16x16x32_bf16 v[10:13], v[226:229], v[182:185], v[10:13]
	v_mfma_f32_16x16x32_bf16 v[6:9], v[218:221], v[190:193], v[6:9]
	v_mfma_f32_16x16x32_bf16 v[2:5], v[226:229], v[190:193], v[2:5]
	v_mfma_f32_16x16x32_bf16 v[46:49], v[222:225], v[170:173], v[46:49]
	v_mfma_f32_16x16x32_bf16 v[42:45], v[244:247], v[170:173], v[42:45]
	v_mfma_f32_16x16x32_bf16 v[30:33], v[222:225], v[178:181], v[30:33]
	v_mfma_f32_16x16x32_bf16 v[26:29], v[244:247], v[178:181], v[26:29]
	v_mfma_f32_16x16x32_bf16 v[14:17], v[222:225], v[186:189], v[14:17]
	v_mfma_f32_16x16x32_bf16 v[10:13], v[244:247], v[186:189], v[10:13]
	v_mfma_f32_16x16x32_bf16 v[6:9], v[222:225], v[214:217], v[6:9]
	v_mfma_f32_16x16x32_bf16 v[2:5], v[244:247], v[214:217], v[2:5]
	s_setprio 0
	s_movk_i32 s2, 0x100
	s_andn2_b64 vcc, exec, s[46:47]
	s_mov_b64 s[48:49], -1
	s_mov_b64 s[46:47], 0
	s_barrier
	s_cbranch_vccz .LBB0_162
; DI unsigned pk2(float lo, float hi) { f32x2 v = {lo, hi}; bf2_t b = __builtin_convertvector(v, bf2_t); return __builtin_bit_cast(unsigned, b); }
;     DI void operator()(const f32x4 (&acc)[2][2][4][2], const Unit& u, int wr, int wc, int fr, int fq) const {
;         const int row0 = u.pm * BM + wr * 64 + fr, col0 = u.pn * BM + wc * 32 + 8 * fq;
; #pragma unroll
;         for (int ai = 0; ai < 2; ++ai)
; #pragma unroll
;             for (int m = 0; m < 4; ++m) { bf16_t* rowp = O + (size_t)(row0 + ai * HALF + m * 16) * ldc + col0;
; #pragma unroll
;                 for (int bj = 0; bj < 2; ++bj) { f32x4 v0 = acc[ai][bj][m][0], v1 = acc[ai][bj][m][1];
;                     if (ACT == 1) {
; #pragma unroll
;                         for (int j = 0; j < 4; ++j) { float a = fmaxf(v0[j], 0.f), b = fmaxf(v1[j], 0.f); v0[j] = a * a; v1[j] = b * b; } }
;                     u32x4 w; w.x = pk2(v0[0], v0[1]); w.y = pk2(v0[2], v0[3]); w.z = pk2(v1[0], v1[1]); w.w = pk2(v1[2], v1[3]);
;                     *(u32x4*)(rowp + bj * HALF) = w; } }
; template <class Epi, class Sched>
; DI void gemm_phase(LAS unsigned char* lds, const Gemm g, const Sched& S, const Epi& E, const int tid) {
;     ...
;         E(acc, cur, wr, wc, fr, fq);
;         if (!has_next) break;
; #pragma unroll
;         for (int a = 0; a < 2; ++a)
; #pragma unroll
;             for (int b = 0; b < 2; ++b)
; #pragma unroll
;                 for (int m = 0; m < 4; ++m)
; #pragma unroll
;                     for (int n = 0; n < 2; ++n) acc[a][b][m][n] = (f32x4){0.f, 0.f, 0.f, 0.f};
;         cur = nxt; cA = nA; cB = nB; ++ui;
	v_readlane_b32 s0, v251, 10
	v_lshl_add_u32 v154, s64, 8, v146
	v_lshl_or_b32 v132, s63, 8, v148
	v_readlane_b32 s1, v251, 11
	v_ashrrev_i32_e32 v133, 31, v132
	v_cvt_pk_bf16_f32 v70, v70, v71
	v_mov_b64_e32 v[150:151], s[0:1]
	v_cvt_pk_bf16_f32 v71, v72, v73
	v_cvt_pk_bf16_f32 v72, v66, v67
	v_add_u32_e32 v66, 0x80, v154
	v_mad_i64_i32 v[152:153], s[0:1], v154, s84, v[150:151]
	v_lshlrev_b64 v[132:133], 1, v[132:133]
	v_cvt_pk_bf16_f32 v110, v110, v111
	v_cvt_pk_bf16_f32 v111, v112, v113
	v_cvt_pk_bf16_f32 v112, v106, v107
	v_or_b32_e32 v106, 16, v154
	v_mad_i64_i32 v[66:67], s[0:1], v66, s84, v[150:151]
	v_cvt_pk_bf16_f32 v46, v46, v47
	v_cvt_pk_bf16_f32 v47, v48, v49
	v_cvt_pk_bf16_f32 v48, v42, v43
	v_add_u32_e32 v42, 0x90, v154
	v_lshl_add_u64 v[152:153], v[152:153], 0, v[132:133]
	v_cvt_pk_bf16_f32 v113, v108, v109
	v_mad_i64_i32 v[106:107], s[0:1], v106, s84, v[150:151]
	v_cvt_pk_bf16_f32 v94, v94, v95
	v_cvt_pk_bf16_f32 v95, v96, v97
	v_cvt_pk_bf16_f32 v96, v90, v91
	v_or_b32_e32 v90, 32, v154
	v_lshl_add_u64 v[66:67], v[66:67], 0, v[132:133]
	v_cvt_pk_bf16_f32 v49, v44, v45
	v_mad_i64_i32 v[42:43], s[0:1], v42, s84, v[150:151]
	v_cvt_pk_bf16_f32 v30, v30, v31
	v_cvt_pk_bf16_f32 v31, v32, v33
	v_cvt_pk_bf16_f32 v32, v26, v27
	v_add_u32_e32 v26, 0xa0, v154
	global_store_dwordx4 v[152:153], v[110:113], off offset:256 nt
	v_cvt_pk_bf16_f32 v97, v92, v93
	v_mad_i64_i32 v[90:91], s[0:1], v90, s84, v[150:151]
	v_lshl_add_u64 v[110:111], v[106:107], 0, v[132:133]
	v_cvt_pk_bf16_f32 v78, v78, v79
	v_cvt_pk_bf16_f32 v79, v80, v81
	v_cvt_pk_bf16_f32 v80, v74, v75
	v_or_b32_e32 v74, 48, v154
	global_store_dwordx4 v[66:67], v[46:49], off offset:256 nt
	v_cvt_pk_bf16_f32 v33, v28, v29
	v_mad_i64_i32 v[26:27], s[0:1], v26, s84, v[150:151]
	v_lshl_add_u64 v[46:47], v[42:43], 0, v[132:133]
	v_cvt_pk_bf16_f32 v14, v14, v15
	v_cvt_pk_bf16_f32 v15, v16, v17
	v_cvt_pk_bf16_f32 v16, v10, v11
	v_add_u32_e32 v10, 0xb0, v154
	global_store_dwordx4 v[110:111], v[94:97], off offset:256 nt
	v_cvt_pk_bf16_f32 v81, v76, v77
	v_mad_i64_i32 v[74:75], s[0:1], v74, s84, v[150:151]
	v_lshl_add_u64 v[94:95], v[90:91], 0, v[132:133]
	global_store_dwordx4 v[46:47], v[30:33], off offset:256 nt
	v_cvt_pk_bf16_f32 v17, v12, v13
	v_mad_i64_i32 v[10:11], s[0:1], v10, s84, v[150:151]
	v_lshl_add_u64 v[30:31], v[26:27], 0, v[132:133]
	v_readlane_b32 s76, v255, 15
	v_readlane_b32 s78, v255, 17
	v_cvt_pk_bf16_f32 v126, v126, v127
	v_cvt_pk_bf16_f32 v127, v128, v129
	v_cvt_pk_bf16_f32 v128, v122, v123
	v_cvt_pk_bf16_f32 v129, v124, v125
	v_cvt_pk_bf16_f32 v106, v118, v119
	v_cvt_pk_bf16_f32 v107, v120, v121
	v_cvt_pk_bf16_f32 v108, v114, v115
	v_cvt_pk_bf16_f32 v109, v116, v117
	v_cvt_pk_bf16_f32 v90, v102, v103
	v_cvt_pk_bf16_f32 v91, v104, v105
	v_cvt_pk_bf16_f32 v92, v98, v99
	v_cvt_pk_bf16_f32 v93, v100, v101
	global_store_dwordx4 v[94:95], v[78:81], off offset:256 nt
	v_cvt_pk_bf16_f32 v76, v82, v83
	v_cvt_pk_bf16_f32 v77, v84, v85
	v_lshl_add_u64 v[78:79], v[74:75], 0, v[132:133]
	v_cvt_pk_bf16_f32 v74, v86, v87
	v_cvt_pk_bf16_f32 v75, v88, v89
	v_cvt_pk_bf16_f32 v73, v68, v69
	v_cvt_pk_bf16_f32 v62, v62, v63
	v_cvt_pk_bf16_f32 v63, v64, v65
	v_cvt_pk_bf16_f32 v64, v58, v59
	v_cvt_pk_bf16_f32 v65, v60, v61
	v_cvt_pk_bf16_f32 v42, v54, v55
	v_cvt_pk_bf16_f32 v43, v56, v57
	v_cvt_pk_bf16_f32 v44, v50, v51
	v_cvt_pk_bf16_f32 v45, v52, v53
	v_cvt_pk_bf16_f32 v26, v38, v39
	v_cvt_pk_bf16_f32 v27, v40, v41
	v_cvt_pk_bf16_f32 v28, v34, v35
	v_cvt_pk_bf16_f32 v29, v36, v37
	global_store_dwordx4 v[30:31], v[14:17], off offset:256 nt
	v_cvt_pk_bf16_f32 v12, v18, v19
	v_cvt_pk_bf16_f32 v13, v20, v21
	v_lshl_add_u64 v[14:15], v[10:11], 0, v[132:133]
	v_cvt_pk_bf16_f32 v10, v22, v23
	v_cvt_pk_bf16_f32 v11, v24, v25
	v_cvt_pk_bf16_f32 v6, v6, v7
	v_cvt_pk_bf16_f32 v7, v8, v9
	v_cvt_pk_bf16_f32 v8, v2, v3
	v_cvt_pk_bf16_f32 v9, v4, v5
	s_and_b64 vcc, exec, s[40:41]
	s_mov_b32 s63, s4
	s_mov_b32 s64, s6
	s_mov_b64 s[0:1], s[42:43]
	s_mov_b64 s[44:45], s[8:9]
	v_readlane_b32 s8, v254, 57
	v_readlane_b32 s77, v255, 16
	v_readlane_b32 s79, v255, 18
	s_mov_b64 s[82:83], 0x58000
	s_mov_b64 s[96:97], 0x2c0000
	global_store_dwordx4 v[152:153], v[126:129], off nt
	global_store_dwordx4 v[110:111], v[106:109], off nt
	global_store_dwordx4 v[94:95], v[90:93], off nt
	global_store_dwordx4 v[78:79], v[74:77], off nt
	global_store_dwordx4 v[78:79], v[70:73], off offset:256 nt
	global_store_dwordx4 v[66:67], v[62:65], off nt
	global_store_dwordx4 v[46:47], v[42:45], off nt
	global_store_dwordx4 v[30:31], v[26:29], off nt
	global_store_dwordx4 v[14:15], v[10:13], off nt
	global_store_dwordx4 v[14:15], v[6:9], off offset:256 nt
	v_readlane_b32 s9, v254, 58
	s_cbranch_vccz .LBB0_155
	s_waitcnt vmcnt(0)
	v_readlane_b32 s0, v255, 35
	v_readlane_b32 s60, v254, 63
	s_cmpk_gt_u32 s0, 0xff
	v_readlane_b32 s61, v255, 0
	v_readlane_b32 s62, v255, 1
	v_readlane_b32 s63, v255, 2
	v_readlane_b32 s64, v255, 3
	v_readlane_b32 s65, v255, 4
	v_readlane_b32 s66, v255, 5
	v_readlane_b32 s67, v255, 6
	v_readlane_b32 s68, v255, 7
	v_readlane_b32 s69, v255, 8
	v_readlane_b32 s70, v255, 9
	v_readlane_b32 s71, v255, 10
	v_readlane_b32 s72, v255, 11
	v_readlane_b32 s73, v255, 12
	v_readlane_b32 s74, v255, 13
	v_readlane_b32 s75, v255, 14
	s_cbranch_scc1 .LBB0_166
	s_barrier

; #define PG8_STAGE(bufoff, gbase, voff) do { _Pragma("unroll") for (int _i = 0; _i < 2; ++_i) \
;         __builtin_amdgcn_global_load_lds((const unsigned*)((const char*)(gbase) + (size_t)_i * p64##voff + (v##voff##_)), (LAS unsigned*)(lds + (bufoff) + ldsw + _i * 8192), 16, 0, 0); } while (0)
; #define PG8_LDA(dst, b, h) do { _Pragma("unroll") for (int m = 0; m < 4; ++m) _Pragma("unroll") for (int k = 0; k < 2; ++k) dst[m][k] = *(const LAS bf16x8*)(lds + PG8_SA(b, h) + aoff + m * 2048 + k * 1024); } while (0)
; #define PG8_LDB(dst, b, h) do { _Pragma("unroll") for (int n = 0; n < 2; ++n) _Pragma("unroll") for (int k = 0; k < 2; ++k) dst[n][k] = *(const LAS bf16x8*)(lds + PG8_SB(b, h) + boff + n * 2048 + k * 1024); } while (0)
; #define PG8_MMA(ai, bj, At, Bt) do { __builtin_amdgcn_s_setprio(1); _Pragma("unroll") for (int m = 0; m < 4; ++m) _Pragma("unroll") for (int n = 0; n < 2; ++n) _Pragma("unroll") for (int k = 0; k < 2; ++k) \
;         acc[ai][bj][m][n] = __builtin_amdgcn_mfma_f32_16x16x32_bf16(Bt[n][k], At[m][k], acc[ai][bj][m][n], 0, 0, 0); __builtin_amdgcn_s_setprio(0); } while (0)
; #define PG8_WAIT_L(n) asm volatile("s_waitcnt lgkmcnt(" #n ")" ::: "memory")
; #define PG8_BAR __builtin_amdgcn_s_barrier()
; #define PG8_SCHED __builtin_amdgcn_sched_barrier(0)
; template <class Epi, class Sched>
; DI void gemm_phase(LAS unsigned char* lds, const Gemm g, const Sched& S, const Epi& E, const int tid) {
;     ...
;             PG8_LDB(B0, 0, 0); PG8_SCHED; PG8_LDA(At, 0, 0); PG8_STAGE(PG8_SA(1, 1), a1 + hstepA, offA);
;             PG8_WAIT_L(8); PG8_BAR; PG8_WAIT_L(0); PG8_MMA(0, 0, At, B0); PG8_BAR; PG8_SCHED;
;             PG8_LDB(B1, 0, 1); PG8_STAGE(PG8_SB(0, 0), b2, offB);
;             PG8_BAR; PG8_WAIT_L(0); PG8_MMA(0, 1, At, B1); PG8_BAR;
;             PG8_LDA(At, 0, 1); PG8_STAGE(PG8_SA(0, 0), a2, offA);
;             PG8_BAR; PG8_WAIT_L(0); PG8_MMA(1, 0, At, B0); PG8_BAR; PG8_SCHED;
.LBB0_180:
	s_add_u32 s45, s0, 0xfffc0080
	s_addc_u32 s60, s1, -1
	s_add_i32 s64, 0, 0x10000
	v_add_u32_e32 v160, s64, v133
	ds_read_b128 v[148:151], v160
	ds_read_b128 v[152:155], v160 offset:1024
	ds_read_b128 v[156:159], v160 offset:2048
	ds_read_b128 v[160:163], v160 offset:3072
	s_cmp_eq_u32 s44, 2
	s_cselect_b32 s61, s5, s60
	s_cselect_b32 s60, s59, s45
	s_cselect_b32 s63, s7, s43
	s_cselect_b32 s62, s6, s42
	v_lshl_add_u64 v[192:193], s[0:1], 0, v[130:131]
	s_add_i32 m0, s49, 0xc000
	ds_read_b128 v[164:167], v147
	ds_read_b128 v[168:171], v147 offset:1024
	ds_read_b128 v[172:175], v147 offset:2048
	ds_read_b128 v[176:179], v147 offset:3072
	ds_read_b128 v[180:183], v147 offset:4096
	ds_read_b128 v[184:187], v147 offset:5120
	ds_read_b128 v[188:191], v147 offset:6144
	ds_read_b128 v[214:217], v147 offset:7168
	global_load_lds_dwordx4 v[192:193], off
	v_lshl_add_u64 v[192:193], v[192:193], 0, s[10:11]
	s_add_i32 m0, s49, 0xe000
	s_nop 0
	global_load_lds_dwordx4 v[192:193], off
	s_waitcnt lgkmcnt(8)
	s_barrier
	s_waitcnt lgkmcnt(0)
	s_setprio 1
	s_waitcnt lgkmcnt(0)
	v_mfma_f32_16x16x32_bf16 v[126:129], v[148:151], v[164:167], v[126:129]
	v_mfma_f32_16x16x32_bf16 v[122:125], v[156:159], v[164:167], v[122:125]
	v_mfma_f32_16x16x32_bf16 v[118:121], v[148:151], v[172:175], v[118:121]
	v_mfma_f32_16x16x32_bf16 v[114:117], v[156:159], v[172:175], v[114:117]
	v_mfma_f32_16x16x32_bf16 v[102:105], v[148:151], v[180:183], v[102:105]
	v_mfma_f32_16x16x32_bf16 v[98:101], v[156:159], v[180:183], v[98:101]
	v_mfma_f32_16x16x32_bf16 v[86:89], v[148:151], v[188:191], v[86:89]
	v_mfma_f32_16x16x32_bf16 v[82:85], v[156:159], v[188:191], v[82:85]
	v_mfma_f32_16x16x32_bf16 v[126:129], v[152:155], v[168:171], v[126:129]
	v_mfma_f32_16x16x32_bf16 v[122:125], v[160:163], v[168:171], v[122:125]
	v_mfma_f32_16x16x32_bf16 v[118:121], v[152:155], v[176:179], v[118:121]
	v_mfma_f32_16x16x32_bf16 v[114:117], v[160:163], v[176:179], v[114:117]
	v_mfma_f32_16x16x32_bf16 v[102:105], v[152:155], v[184:187], v[102:105]
	v_mfma_f32_16x16x32_bf16 v[98:101], v[160:163], v[184:187], v[98:101]
	v_mfma_f32_16x16x32_bf16 v[86:89], v[152:155], v[214:217], v[86:89]
	v_mfma_f32_16x16x32_bf16 v[82:85], v[160:163], v[214:217], v[82:85]
	s_setprio 0
	s_barrier
	s_add_i32 s45, 0, 0x14000
	v_add_u32_e32 v192, s45, v133
	ds_read_b128 v[218:221], v192
	ds_read_b128 v[222:225], v192 offset:1024
	ds_read_b128 v[226:229], v192 offset:2048
	ds_read_b128 v[244:247], v192 offset:3072
	v_lshl_add_u64 v[192:193], s[62:63], 0, v[0:1]
	s_add_i32 s62, s64, s48
	s_mov_b32 m0, s62
	v_lshl_add_u64 v[198:199], v[192:193], 0, s[68:69]
	global_load_lds_dwordx4 v[192:193], off
	s_add_i32 m0, s62, 0x2000
	s_nop 0
	global_load_lds_dwordx4 v[198:199], off
	s_barrier
	s_waitcnt lgkmcnt(0)
	s_setprio 1
	s_waitcnt lgkmcnt(0)
	v_mfma_f32_16x16x32_bf16 v[110:113], v[218:221], v[164:167], v[110:113]
	v_mfma_f32_16x16x32_bf16 v[106:109], v[226:229], v[164:167], v[106:109]
	v_mfma_f32_16x16x32_bf16 v[94:97], v[218:221], v[172:175], v[94:97]
	v_mfma_f32_16x16x32_bf16 v[90:93], v[226:229], v[172:175], v[90:93]
	v_mfma_f32_16x16x32_bf16 v[78:81], v[218:221], v[180:183], v[78:81]
	v_mfma_f32_16x16x32_bf16 v[74:77], v[226:229], v[180:183], v[74:77]
	v_mfma_f32_16x16x32_bf16 v[70:73], v[218:221], v[188:191], v[70:73]
	v_mfma_f32_16x16x32_bf16 v[66:69], v[226:229], v[188:191], v[66:69]
	v_mfma_f32_16x16x32_bf16 v[110:113], v[222:225], v[168:171], v[110:113]
	v_mfma_f32_16x16x32_bf16 v[106:109], v[244:247], v[168:171], v[106:109]
	v_mfma_f32_16x16x32_bf16 v[94:97], v[222:225], v[176:179], v[94:97]
	v_mfma_f32_16x16x32_bf16 v[90:93], v[244:247], v[176:179], v[90:93]
	v_mfma_f32_16x16x32_bf16 v[78:81], v[222:225], v[184:187], v[78:81]
	v_mfma_f32_16x16x32_bf16 v[74:77], v[244:247], v[184:187], v[74:77]
	v_mfma_f32_16x16x32_bf16 v[70:73], v[222:225], v[214:217], v[70:73]
	v_mfma_f32_16x16x32_bf16 v[66:69], v[244:247], v[214:217], v[66:69]
	s_setprio 0
	s_mov_b32 m0, s49
	v_lshl_add_u64 v[198:199], s[60:61], 0, v[212:213]
	s_barrier
	ds_read_b128 v[164:167], v147 offset:16384
	ds_read_b128 v[168:171], v147 offset:17408
	ds_read_b128 v[172:175], v147 offset:18432
	ds_read_b128 v[176:179], v147 offset:19456
	ds_read_b128 v[180:183], v147 offset:20480
	ds_read_b128 v[184:187], v147 offset:21504
	ds_read_b128 v[188:191], v147 offset:22528
	ds_read_b128 v[214:217], v147 offset:23552
	global_load_lds_dwordx4 v[198:199], off
	v_lshl_add_u64 v[200:201], v[198:199], 0, s[10:11]
	s_mov_b32 m0, s50
	s_nop 0
	global_load_lds_dwordx4 v[200:201], off
	s_barrier
	s_waitcnt lgkmcnt(0)
	s_setprio 1
	s_waitcnt lgkmcnt(0)
	v_mfma_f32_16x16x32_bf16 v[62:65], v[148:151], v[164:167], v[62:65]
	v_mfma_f32_16x16x32_bf16 v[58:61], v[156:159], v[164:167], v[58:61]
	v_mfma_f32_16x16x32_bf16 v[54:57], v[148:151], v[172:175], v[54:57]
	v_mfma_f32_16x16x32_bf16 v[50:53], v[156:159], v[172:175], v[50:53]
	v_mfma_f32_16x16x32_bf16 v[38:41], v[148:151], v[180:183], v[38:41]
	v_mfma_f32_16x16x32_bf16 v[34:37], v[156:159], v[180:183], v[34:37]
	v_mfma_f32_16x16x32_bf16 v[22:25], v[148:151], v[188:191], v[22:25]
	v_mfma_f32_16x16x32_bf16 v[18:21], v[156:159], v[188:191], v[18:21]
	v_mfma_f32_16x16x32_bf16 v[62:65], v[152:155], v[168:171], v[62:65]
	v_mfma_f32_16x16x32_bf16 v[58:61], v[160:163], v[168:171], v[58:61]
	v_mfma_f32_16x16x32_bf16 v[54:57], v[152:155], v[176:179], v[54:57]
	v_mfma_f32_16x16x32_bf16 v[50:53], v[160:163], v[176:179], v[50:53]
	v_mfma_f32_16x16x32_bf16 v[38:41], v[152:155], v[184:187], v[38:41]
	v_mfma_f32_16x16x32_bf16 v[34:37], v[160:163], v[184:187], v[34:37]
	v_mfma_f32_16x16x32_bf16 v[22:25], v[152:155], v[214:217], v[22:25]
	v_mfma_f32_16x16x32_bf16 v[18:21], v[160:163], v[214:217], v[18:21]
	s_setprio 0
	s_barrier
; #define PG8_STAGE(bufoff, gbase, voff) do { _Pragma("unroll") for (int _i = 0; _i < 2; ++_i) \
;         __builtin_amdgcn_global_load_lds((const unsigned*)((const char*)(gbase) + (size_t)_i * p64##voff + (v##voff##_)), (LAS unsigned*)(lds + (bufoff) + ldsw + _i * 8192), 16, 0, 0); } while (0)
; #define PG8_LDA(dst, b, h) do { _Pragma("unroll") for (int m = 0; m < 4; ++m) _Pragma("unroll") for (int k = 0; k < 2; ++k) dst[m][k] = *(const LAS bf16x8*)(lds + PG8_SA(b, h) + aoff + m * 2048 + k * 1024); } while (0)
; #define PG8_LDB(dst, b, h) do { _Pragma("unroll") for (int n = 0; n < 2; ++n) _Pragma("unroll") for (int k = 0; k < 2; ++k) dst[n][k] = *(const LAS bf16x8*)(lds + PG8_SB(b, h) + boff + n * 2048 + k * 1024); } while (0)
; #define PG8_MMA(ai, bj, At, Bt) do { __builtin_amdgcn_s_setprio(1); _Pragma("unroll") for (int m = 0; m < 4; ++m) _Pragma("unroll") for (int n = 0; n < 2; ++n) _Pragma("unroll") for (int k = 0; k < 2; ++k) \
;         acc[ai][bj][m][n] = __builtin_amdgcn_mfma_f32_16x16x32_bf16(Bt[n][k], At[m][k], acc[ai][bj][m][n], 0, 0, 0); __builtin_amdgcn_s_setprio(0); } while (0)
; #define PG8_WAIT_V(n) asm volatile("s_waitcnt vmcnt(" #n ")" ::: "memory")
; #define PG8_WAIT_L(n) asm volatile("s_waitcnt lgkmcnt(" #n ")" ::: "memory")
; #define PG8_BAR __builtin_amdgcn_s_barrier()
; #define PG8_SCHED __builtin_amdgcn_sched_barrier(0)
; template <class Epi, class Sched>
; DI void gemm_phase(LAS unsigned char* lds, const Gemm g, const Sched& S, const Epi& E, const int tid) {
;     ...
;             PG8_STAGE(PG8_SB(0, 1), b2 + hstepB, offB);
;             PG8_WAIT_V(6); PG8_BAR; PG8_MMA(1, 1, At, B1); PG8_BAR;
;             PG8_LDB(B0, 1, 0); PG8_SCHED; PG8_LDA(At, 1, 0); PG8_STAGE(PG8_SA(0, 1), a2 + hstepA, offA);
;             PG8_WAIT_L(8); PG8_BAR; PG8_WAIT_L(0); PG8_MMA(0, 0, At, B0); PG8_BAR; PG8_SCHED;
;             PG8_LDB(B1, 1, 1); PG8_STAGE(PG8_SB(1, 0), b3, offB);
;             PG8_BAR; PG8_WAIT_L(0); PG8_MMA(0, 1, At, B1); PG8_BAR;
;             PG8_LDA(At, 1, 1); PG8_STAGE(PG8_SA(1, 0), a3, offA);
	s_add_i32 s45, s45, s48
	v_lshl_add_u64 v[148:149], v[192:193], 0, s[38:39]
	s_mov_b32 m0, s45
	s_nop 0
	global_load_lds_dwordx4 v[148:149], off
	v_lshl_add_u64 v[148:149], v[192:193], 0, s[70:71]
	s_add_i32 m0, s45, 0x2000
	s_nop 0
	global_load_lds_dwordx4 v[148:149], off
	s_waitcnt vmcnt(6)
	s_barrier
	s_setprio 1
	v_mfma_f32_16x16x32_bf16 v[46:49], v[218:221], v[164:167], v[46:49]
	v_mfma_f32_16x16x32_bf16 v[42:45], v[226:229], v[164:167], v[42:45]
	v_mfma_f32_16x16x32_bf16 v[30:33], v[218:221], v[172:175], v[30:33]
	v_mfma_f32_16x16x32_bf16 v[26:29], v[226:229], v[172:175], v[26:29]
	v_mfma_f32_16x16x32_bf16 v[14:17], v[218:221], v[180:183], v[14:17]
	v_mfma_f32_16x16x32_bf16 v[10:13], v[226:229], v[180:183], v[10:13]
	v_mfma_f32_16x16x32_bf16 v[6:9], v[218:221], v[188:191], v[6:9]
	v_mfma_f32_16x16x32_bf16 v[2:5], v[226:229], v[188:191], v[2:5]
	v_mfma_f32_16x16x32_bf16 v[46:49], v[222:225], v[168:171], v[46:49]
	v_mfma_f32_16x16x32_bf16 v[42:45], v[244:247], v[168:171], v[42:45]
	v_mfma_f32_16x16x32_bf16 v[30:33], v[222:225], v[176:179], v[30:33]
	v_mfma_f32_16x16x32_bf16 v[26:29], v[244:247], v[176:179], v[26:29]
	v_mfma_f32_16x16x32_bf16 v[14:17], v[222:225], v[184:187], v[14:17]
	v_mfma_f32_16x16x32_bf16 v[10:13], v[244:247], v[184:187], v[10:13]
	v_mfma_f32_16x16x32_bf16 v[6:9], v[222:225], v[214:217], v[6:9]
	v_mfma_f32_16x16x32_bf16 v[2:5], v[244:247], v[214:217], v[2:5]
	s_setprio 0
	s_add_i32 s45, 0, 0x18000
	v_add_u32_e32 v160, s45, v133
	s_barrier
	ds_read_b128 v[148:151], v160
	ds_read_b128 v[152:155], v160 offset:1024
	ds_read_b128 v[156:159], v160 offset:2048
	ds_read_b128 v[160:163], v160 offset:3072
	s_mov_b32 m0, s51
	v_lshl_add_u64 v[200:201], v[198:199], 0, s[24:25]
	ds_read_b128 v[164:167], v147 offset:32768
	ds_read_b128 v[168:171], v147 offset:33792
	ds_read_b128 v[172:175], v147 offset:34816
	ds_read_b128 v[176:179], v147 offset:35840
	ds_read_b128 v[180:183], v147 offset:36864
	ds_read_b128 v[184:187], v147 offset:37888
	ds_read_b128 v[188:191], v147 offset:38912
	ds_read_b128 v[214:217], v147 offset:39936
	global_load_lds_dwordx4 v[200:201], off
	v_lshl_add_u64 v[200:201], v[198:199], 0, s[28:29]
	s_mov_b32 m0, s52
	s_nop 0
	global_load_lds_dwordx4 v[200:201], off
	s_waitcnt lgkmcnt(8)
	s_barrier
	s_waitcnt lgkmcnt(0)
	s_setprio 1
	s_waitcnt lgkmcnt(0)
	v_mfma_f32_16x16x32_bf16 v[126:129], v[148:151], v[164:167], v[126:129]
	v_mfma_f32_16x16x32_bf16 v[122:125], v[156:159], v[164:167], v[122:125]
	v_mfma_f32_16x16x32_bf16 v[118:121], v[148:151], v[172:175], v[118:121]
	v_mfma_f32_16x16x32_bf16 v[114:117], v[156:159], v[172:175], v[114:117]
	v_mfma_f32_16x16x32_bf16 v[102:105], v[148:151], v[180:183], v[102:105]
	v_mfma_f32_16x16x32_bf16 v[98:101], v[156:159], v[180:183], v[98:101]
	v_mfma_f32_16x16x32_bf16 v[86:89], v[148:151], v[188:191], v[86:89]
	v_mfma_f32_16x16x32_bf16 v[82:85], v[156:159], v[188:191], v[82:85]
	v_mfma_f32_16x16x32_bf16 v[126:129], v[152:155], v[168:171], v[126:129]
	v_mfma_f32_16x16x32_bf16 v[122:125], v[160:163], v[168:171], v[122:125]
	v_mfma_f32_16x16x32_bf16 v[118:121], v[152:155], v[176:179], v[118:121]
	v_mfma_f32_16x16x32_bf16 v[114:117], v[160:163], v[176:179], v[114:117]
	v_mfma_f32_16x16x32_bf16 v[102:105], v[152:155], v[184:187], v[102:105]
	v_mfma_f32_16x16x32_bf16 v[98:101], v[160:163], v[184:187], v[98:101]
	v_mfma_f32_16x16x32_bf16 v[86:89], v[152:155], v[214:217], v[86:89]
	v_mfma_f32_16x16x32_bf16 v[82:85], v[160:163], v[214:217], v[82:85]
	s_setprio 0
	s_barrier
	s_add_i32 s60, 0, 0x1c000
	v_add_u32_e32 v200, s60, v133
	s_add_i32 s45, s45, s48
	ds_read_b128 v[218:221], v200
	ds_read_b128 v[222:225], v200 offset:1024
	ds_read_b128 v[226:229], v200 offset:2048
	ds_read_b128 v[244:247], v200 offset:3072
	v_lshl_add_u64 v[200:201], v[192:193], 0, s[26:27]
	s_mov_b32 m0, s45
	s_nop 0
	global_load_lds_dwordx4 v[200:201], off
	v_lshl_add_u64 v[200:201], v[192:193], 0, s[72:73]
	s_add_i32 m0, s45, 0x2000
	s_nop 0
	global_load_lds_dwordx4 v[200:201], off
	s_barrier
	s_waitcnt lgkmcnt(0)
	s_setprio 1
	s_waitcnt lgkmcnt(0)
	v_mfma_f32_16x16x32_bf16 v[110:113], v[218:221], v[164:167], v[110:113]
	v_mfma_f32_16x16x32_bf16 v[106:109], v[226:229], v[164:167], v[106:109]
	v_mfma_f32_16x16x32_bf16 v[94:97], v[218:221], v[172:175], v[94:97]
	v_mfma_f32_16x16x32_bf16 v[90:93], v[226:229], v[172:175], v[90:93]
	v_mfma_f32_16x16x32_bf16 v[78:81], v[218:221], v[180:183], v[78:81]
	v_mfma_f32_16x16x32_bf16 v[74:77], v[226:229], v[180:183], v[74:77]
	v_mfma_f32_16x16x32_bf16 v[70:73], v[218:221], v[188:191], v[70:73]
	v_mfma_f32_16x16x32_bf16 v[66:69], v[226:229], v[188:191], v[66:69]
	v_mfma_f32_16x16x32_bf16 v[110:113], v[222:225], v[168:171], v[110:113]
	v_mfma_f32_16x16x32_bf16 v[106:109], v[244:247], v[168:171], v[106:109]
	v_mfma_f32_16x16x32_bf16 v[94:97], v[222:225], v[176:179], v[94:97]
	v_mfma_f32_16x16x32_bf16 v[90:93], v[244:247], v[176:179], v[90:93]
	v_mfma_f32_16x16x32_bf16 v[78:81], v[222:225], v[184:187], v[78:81]
	v_mfma_f32_16x16x32_bf16 v[74:77], v[244:247], v[184:187], v[74:77]
	v_mfma_f32_16x16x32_bf16 v[70:73], v[222:225], v[214:217], v[70:73]
	v_mfma_f32_16x16x32_bf16 v[66:69], v[244:247], v[214:217], v[66:69]
	s_setprio 0
	s_mov_b32 m0, s53
	v_lshl_add_u64 v[200:201], v[198:199], 0, s[26:27]
	s_barrier
	ds_read_b128 v[164:167], v147 offset:49152
	ds_read_b128 v[168:171], v147 offset:50176
	ds_read_b128 v[172:175], v147 offset:51200
	ds_read_b128 v[176:179], v147 offset:52224
	ds_read_b128 v[180:183], v147 offset:53248
	ds_read_b128 v[184:187], v147 offset:54272
	ds_read_b128 v[188:191], v147 offset:55296
	ds_read_b128 v[214:217], v147 offset:56320
	global_load_lds_dwordx4 v[200:201], off
	v_lshl_add_u64 v[198:199], v[198:199], 0, s[36:37]
	s_mov_b32 m0, s54
	s_nop 0
	global_load_lds_dwordx4 v[198:199], off
	s_barrier
; #define PG8_STAGE(bufoff, gbase, voff) do { _Pragma("unroll") for (int _i = 0; _i < 2; ++_i) \
;         __builtin_amdgcn_global_load_lds((const unsigned*)((const char*)(gbase) + (size_t)_i * p64##voff + (v##voff##_)), (LAS unsigned*)(lds + (bufoff) + ldsw + _i * 8192), 16, 0, 0); } while (0)
; #define PG8_MMA(ai, bj, At, Bt) do { __builtin_amdgcn_s_setprio(1); _Pragma("unroll") for (int m = 0; m < 4; ++m) _Pragma("unroll") for (int n = 0; n < 2; ++n) _Pragma("unroll") for (int k = 0; k < 2; ++k) \
;         acc[ai][bj][m][n] = __builtin_amdgcn_mfma_f32_16x16x32_bf16(Bt[n][k], At[m][k], acc[ai][bj][m][n], 0, 0, 0); __builtin_amdgcn_s_setprio(0); } while (0)
; #define PG8_WAIT_V(n) asm volatile("s_waitcnt vmcnt(" #n ")" ::: "memory")
; #define PG8_WAIT_L(n) asm volatile("s_waitcnt lgkmcnt(" #n ")" ::: "memory")
; #define PG8_BAR __builtin_amdgcn_s_barrier()
; #define PG8_SCHED __builtin_amdgcn_sched_barrier(0)
; template <class Epi, class Sched>
; DI void gemm_phase(LAS unsigned char* lds, const Gemm g, const Sched& S, const Epi& E, const int tid) {
;     ...
;             PG8_BAR; PG8_WAIT_L(0); PG8_MMA(1, 0, At, B0); PG8_BAR; PG8_SCHED;
;             PG8_STAGE(PG8_SB(1, 1), b3 + hstepB, offB);
;             PG8_WAIT_V(6); PG8_BAR; PG8_MMA(1, 1, At, B1); PG8_BAR;
;         }
	s_waitcnt lgkmcnt(0)
	s_setprio 1
	s_waitcnt lgkmcnt(0)
	v_mfma_f32_16x16x32_bf16 v[62:65], v[148:151], v[164:167], v[62:65]
	v_mfma_f32_16x16x32_bf16 v[58:61], v[156:159], v[164:167], v[58:61]
	v_mfma_f32_16x16x32_bf16 v[54:57], v[148:151], v[172:175], v[54:57]
	v_mfma_f32_16x16x32_bf16 v[50:53], v[156:159], v[172:175], v[50:53]
	v_mfma_f32_16x16x32_bf16 v[38:41], v[148:151], v[180:183], v[38:41]
	v_mfma_f32_16x16x32_bf16 v[34:37], v[156:159], v[180:183], v[34:37]
	v_mfma_f32_16x16x32_bf16 v[22:25], v[148:151], v[188:191], v[22:25]
	v_mfma_f32_16x16x32_bf16 v[18:21], v[156:159], v[188:191], v[18:21]
	v_mfma_f32_16x16x32_bf16 v[62:65], v[152:155], v[168:171], v[62:65]
	v_mfma_f32_16x16x32_bf16 v[58:61], v[160:163], v[168:171], v[58:61]
	v_mfma_f32_16x16x32_bf16 v[54:57], v[152:155], v[176:179], v[54:57]
	v_mfma_f32_16x16x32_bf16 v[50:53], v[160:163], v[176:179], v[50:53]
	v_mfma_f32_16x16x32_bf16 v[38:41], v[152:155], v[184:187], v[38:41]
	v_mfma_f32_16x16x32_bf16 v[34:37], v[160:163], v[184:187], v[34:37]
	v_mfma_f32_16x16x32_bf16 v[22:25], v[152:155], v[214:217], v[22:25]
	v_mfma_f32_16x16x32_bf16 v[18:21], v[160:163], v[214:217], v[18:21]
	s_setprio 0
	s_barrier
	s_add_i32 s45, s60, s48
	v_lshl_add_u64 v[148:149], v[192:193], 0, s[66:67]
	s_mov_b32 m0, s45
	s_nop 0
	global_load_lds_dwordx4 v[148:149], off
	v_lshl_add_u64 v[148:149], v[192:193], 0, s[74:75]
	s_add_i32 m0, s45, 0x2000
	s_nop 0
	global_load_lds_dwordx4 v[148:149], off
	s_waitcnt vmcnt(6)
	s_barrier
	s_setprio 1
	v_mfma_f32_16x16x32_bf16 v[46:49], v[218:221], v[164:167], v[46:49]
	v_mfma_f32_16x16x32_bf16 v[42:45], v[226:229], v[164:167], v[42:45]
	v_mfma_f32_16x16x32_bf16 v[30:33], v[218:221], v[172:175], v[30:33]
	v_mfma_f32_16x16x32_bf16 v[26:29], v[226:229], v[172:175], v[26:29]
	v_mfma_f32_16x16x32_bf16 v[14:17], v[218:221], v[180:183], v[14:17]
	v_mfma_f32_16x16x32_bf16 v[10:13], v[226:229], v[180:183], v[10:13]
	v_mfma_f32_16x16x32_bf16 v[6:9], v[218:221], v[188:191], v[6:9]
	v_mfma_f32_16x16x32_bf16 v[2:5], v[226:229], v[188:191], v[2:5]
	v_mfma_f32_16x16x32_bf16 v[46:49], v[222:225], v[168:171], v[46:49]
	v_mfma_f32_16x16x32_bf16 v[42:45], v[244:247], v[168:171], v[42:45]
	v_mfma_f32_16x16x32_bf16 v[30:33], v[222:225], v[176:179], v[30:33]
	v_mfma_f32_16x16x32_bf16 v[26:29], v[244:247], v[176:179], v[26:29]
	v_mfma_f32_16x16x32_bf16 v[14:17], v[222:225], v[184:187], v[14:17]
	v_mfma_f32_16x16x32_bf16 v[10:13], v[244:247], v[184:187], v[10:13]
	v_mfma_f32_16x16x32_bf16 v[6:9], v[222:225], v[214:217], v[6:9]
	v_mfma_f32_16x16x32_bf16 v[2:5], v[244:247], v[214:217], v[2:5]
	s_setprio 0
	s_add_i32 s44, s44, 2
	s_add_u32 s0, s0, 0x100
	s_addc_u32 s1, s1, 0
	s_add_u32 s42, s42, 0x100
	s_addc_u32 s43, s43, 0
	s_cmp_gt_u32 s44, 3
	s_barrier
	s_cbranch_scc0 .LBB0_180
; DI unsigned pk2(float lo, float hi) { f32x2 v = {lo, hi}; bf2_t b = __builtin_convertvector(v, bf2_t); return __builtin_bit_cast(unsigned, b); }
; #define PG8_WAIT_V(n) asm volatile("s_waitcnt vmcnt(" #n ")" ::: "memory")
; #define PG8_BAR __builtin_amdgcn_s_barrier()
;     DI void operator()(const f32x4 (&acc)[2][2][4][2], const Unit& u, int wr, int wc, int fr, int fq) const {
;         const int row0 = u.pm * BM + wr * 64 + fr, col0 = u.pn * BM + wc * 32 + 8 * fq;
; #pragma unroll
;         for (int ai = 0; ai < 2; ++ai)
; #pragma unroll
;             for (int m = 0; m < 4; ++m) { bf16_t* rowp = O + (size_t)(row0 + ai * HALF + m * 16) * ldc + col0;
; #pragma unroll
;                 for (int bj = 0; bj < 2; ++bj) { f32x4 v0 = acc[ai][bj][m][0], v1 = acc[ai][bj][m][1];
;                     if (ACT == 1) {
; #pragma unroll
;                         for (int j = 0; j < 4; ++j) { float a = fmaxf(v0[j], 0.f), b = fmaxf(v1[j], 0.f); v0[j] = a * a; v1[j] = b * b; } }
;                     u32x4 w; w.x = pk2(v0[0], v0[1]); w.y = pk2(v0[2], v0[3]); w.z = pk2(v1[0], v1[1]); w.w = pk2(v1[2], v1[3]);
;                     *(u32x4*)(rowp + bj * HALF) = w; } }
; template <class Epi, class Sched>
; DI void gemm_phase(LAS unsigned char* lds, const Gemm g, const Sched& S, const Epi& E, const int tid) {
;     ...
;         E(acc, cur, wr, wc, fr, fq);
;         if (!has_next) break;
; #pragma unroll
;         for (int a = 0; a < 2; ++a)
; #pragma unroll
;             for (int b = 0; b < 2; ++b)
; #pragma unroll
;                 for (int m = 0; m < 4; ++m)
; #pragma unroll
;                     for (int n = 0; n < 2; ++n) acc[a][b][m][n] = (f32x4){0.f, 0.f, 0.f, 0.f};
;         cur = nxt; cA = nA; cB = nB; ++ui;
;     }
;     PG8_WAIT_V(0);
;     if (wr == 0) PG8_BAR;
;     PG8_BAR;
	v_readlane_b32 s0, v251, 12
	v_lshl_add_u32 v154, s58, 8, v132
	v_lshl_or_b32 v148, s57, 8, v146
	v_readlane_b32 s1, v251, 13
	v_ashrrev_i32_e32 v149, 31, v148
	v_cvt_pk_bf16_f32 v70, v70, v71
	v_mov_b64_e32 v[150:151], s[0:1]
	v_cvt_pk_bf16_f32 v71, v72, v73
	v_cvt_pk_bf16_f32 v72, v66, v67
	v_add_u32_e32 v66, 0x80, v154
	v_mad_i64_i32 v[152:153], s[0:1], v154, s84, v[150:151]
	v_lshlrev_b64 v[148:149], 1, v[148:149]
	v_cvt_pk_bf16_f32 v110, v110, v111
	v_cvt_pk_bf16_f32 v111, v112, v113
	v_cvt_pk_bf16_f32 v112, v106, v107
	v_or_b32_e32 v106, 16, v154
	v_mad_i64_i32 v[66:67], s[0:1], v66, s84, v[150:151]
	v_cvt_pk_bf16_f32 v46, v46, v47
	v_cvt_pk_bf16_f32 v47, v48, v49
	v_cvt_pk_bf16_f32 v48, v42, v43
	v_add_u32_e32 v42, 0x90, v154
	v_lshl_add_u64 v[152:153], v[152:153], 0, v[148:149]
	v_cvt_pk_bf16_f32 v113, v108, v109
	v_mad_i64_i32 v[106:107], s[0:1], v106, s84, v[150:151]
	v_cvt_pk_bf16_f32 v94, v94, v95
	v_cvt_pk_bf16_f32 v95, v96, v97
	v_cvt_pk_bf16_f32 v96, v90, v91
	v_or_b32_e32 v90, 32, v154
	v_lshl_add_u64 v[66:67], v[66:67], 0, v[148:149]
	v_cvt_pk_bf16_f32 v49, v44, v45
	v_mad_i64_i32 v[42:43], s[0:1], v42, s84, v[150:151]
	v_cvt_pk_bf16_f32 v30, v30, v31
	v_cvt_pk_bf16_f32 v31, v32, v33
	v_cvt_pk_bf16_f32 v32, v26, v27
	v_add_u32_e32 v26, 0xa0, v154
	global_store_dwordx4 v[152:153], v[110:113], off offset:256 nt
	v_cvt_pk_bf16_f32 v97, v92, v93
	v_mad_i64_i32 v[90:91], s[0:1], v90, s84, v[150:151]
	v_lshl_add_u64 v[110:111], v[106:107], 0, v[148:149]
	v_cvt_pk_bf16_f32 v78, v78, v79
	v_cvt_pk_bf16_f32 v79, v80, v81
	v_cvt_pk_bf16_f32 v80, v74, v75
	v_or_b32_e32 v74, 48, v154
	global_store_dwordx4 v[66:67], v[46:49], off offset:256 nt
	v_cvt_pk_bf16_f32 v33, v28, v29
	v_mad_i64_i32 v[26:27], s[0:1], v26, s84, v[150:151]
	v_lshl_add_u64 v[46:47], v[42:43], 0, v[148:149]
	v_cvt_pk_bf16_f32 v14, v14, v15
	v_cvt_pk_bf16_f32 v15, v16, v17
	v_cvt_pk_bf16_f32 v16, v10, v11
	v_add_u32_e32 v10, 0xb0, v154
	global_store_dwordx4 v[110:111], v[94:97], off offset:256 nt
	v_cvt_pk_bf16_f32 v81, v76, v77
	v_mad_i64_i32 v[74:75], s[0:1], v74, s84, v[150:151]
	v_lshl_add_u64 v[94:95], v[90:91], 0, v[148:149]
	global_store_dwordx4 v[46:47], v[30:33], off offset:256 nt
	v_cvt_pk_bf16_f32 v17, v12, v13
	v_mad_i64_i32 v[10:11], s[0:1], v10, s84, v[150:151]
	v_lshl_add_u64 v[30:31], v[26:27], 0, v[148:149]
	v_readlane_b32 s60, v254, 63
	v_cvt_pk_bf16_f32 v126, v126, v127
	v_cvt_pk_bf16_f32 v127, v128, v129
	v_cvt_pk_bf16_f32 v128, v122, v123
	v_cvt_pk_bf16_f32 v129, v124, v125
	v_cvt_pk_bf16_f32 v106, v118, v119
	v_cvt_pk_bf16_f32 v107, v120, v121
	v_cvt_pk_bf16_f32 v108, v114, v115
	v_cvt_pk_bf16_f32 v109, v116, v117
	v_cvt_pk_bf16_f32 v90, v102, v103
	v_cvt_pk_bf16_f32 v91, v104, v105
	v_cvt_pk_bf16_f32 v92, v98, v99
	v_cvt_pk_bf16_f32 v93, v100, v101
	global_store_dwordx4 v[94:95], v[78:81], off offset:256 nt
	v_cvt_pk_bf16_f32 v76, v82, v83
	v_cvt_pk_bf16_f32 v77, v84, v85
	v_lshl_add_u64 v[78:79], v[74:75], 0, v[148:149]
	v_cvt_pk_bf16_f32 v74, v86, v87
	v_cvt_pk_bf16_f32 v75, v88, v89
	v_cvt_pk_bf16_f32 v73, v68, v69
	v_cvt_pk_bf16_f32 v62, v62, v63
	v_cvt_pk_bf16_f32 v63, v64, v65
	v_cvt_pk_bf16_f32 v64, v58, v59
	v_cvt_pk_bf16_f32 v65, v60, v61
	v_cvt_pk_bf16_f32 v42, v54, v55
	v_cvt_pk_bf16_f32 v43, v56, v57
	v_cvt_pk_bf16_f32 v44, v50, v51
	v_cvt_pk_bf16_f32 v45, v52, v53
	v_cvt_pk_bf16_f32 v26, v38, v39
	v_cvt_pk_bf16_f32 v27, v40, v41
	v_cvt_pk_bf16_f32 v28, v34, v35
	v_cvt_pk_bf16_f32 v29, v36, v37
	global_store_dwordx4 v[30:31], v[14:17], off offset:256 nt
	v_cvt_pk_bf16_f32 v12, v18, v19
	v_cvt_pk_bf16_f32 v13, v20, v21
	v_lshl_add_u64 v[14:15], v[10:11], 0, v[148:149]
	v_cvt_pk_bf16_f32 v10, v22, v23
	v_cvt_pk_bf16_f32 v11, v24, v25
	v_cvt_pk_bf16_f32 v6, v6, v7
	v_cvt_pk_bf16_f32 v7, v8, v9
	v_cvt_pk_bf16_f32 v8, v2, v3
	v_cvt_pk_bf16_f32 v9, v4, v5
	s_and_b64 vcc, exec, s[40:41]
	s_mov_b32 s57, s56
	s_mov_b32 s58, s4
	s_mov_b64 s[42:43], s[6:7]
	s_mov_b64 s[44:45], s[8:9]
	v_readlane_b32 s61, v255, 0
	v_readlane_b32 s62, v255, 1
	v_readlane_b32 s63, v255, 2
	v_readlane_b32 s64, v255, 3
	v_readlane_b32 s65, v255, 4
	v_readlane_b32 s66, v255, 5
	v_readlane_b32 s67, v255, 6
	v_readlane_b32 s68, v255, 7
	v_readlane_b32 s69, v255, 8
	v_readlane_b32 s70, v255, 9
	v_readlane_b32 s71, v255, 10
	v_readlane_b32 s72, v255, 11
	v_readlane_b32 s73, v255, 12
	v_readlane_b32 s74, v255, 13
	v_readlane_b32 s75, v255, 14
	global_store_dwordx4 v[152:153], v[126:129], off nt
	global_store_dwordx4 v[110:111], v[106:109], off nt
	global_store_dwordx4 v[94:95], v[90:93], off nt
	global_store_dwordx4 v[78:79], v[74:77], off nt
	global_store_dwordx4 v[78:79], v[70:73], off offset:256 nt
	global_store_dwordx4 v[66:67], v[62:65], off nt
	global_store_dwordx4 v[46:47], v[42:45], off nt
	global_store_dwordx4 v[30:31], v[26:29], off nt
	global_store_dwordx4 v[14:15], v[10:13], off nt
	global_store_dwordx4 v[14:15], v[6:9], off offset:256 nt
	s_cbranch_vccz .LBB0_171
	s_waitcnt vmcnt(0)
	v_readlane_b32 s84, v254, 59
	s_cmpk_gt_u32 s2, 0xff
	v_readlane_b32 s85, v254, 60
	s_cbranch_scc1 .LBB0_184
	s_barrier
